# norm-phase loops P0/P2.5/P4/P7: gamma vectors hoisted out of the row loops, per-store vmcnt(0) drains replaced by counted waits
# speedup vs baseline: 1.0640x; 1.0187x over previous
; __global__ void __launch_bounds__(NTHR, 2) hymba_fwd(Params P) {
;     ...
;         for (int t0 = gw; t0 < TT; t0 += 2 * NGW) {
;             f32x4 v[2][4]; int tt[2];
; #pragma unroll
;             for (int u = 0; u < 2; ++u) { const int t = t0 + u * NGW; tt[u] = t; const int tc = t < TT ? t : TT - 1;
;                 const int b = tc / LL, p = tc - b * LL;
;                 const float* src = (p < NMETA) ? P.meta + (size_t)p * 1024 : P.x + ((size_t)b * SEQ + p - NMETA) * 1024;
; #pragma unroll
;                 for (int j = 0; j < 4; ++j) v[u][j] = __builtin_nontemporal_load((const f32x4*)src + lane + 64 * j); }
; #pragma unroll
;             for (int u = 0; u < 2; ++u) { const int t = tt[u];
;                 if (t < TT) rms_store_bf16(v[u], P.mix_pre_g, XN + (size_t)t * 1024, lane); }
.LBB0_36:
	v_readlane_b32 s4, v237, 0
	v_readlane_b32 s5, v237, 1
	v_readlane_b32 s6, v237, 2
	v_readlane_b32 s7, v237, 3
	v_readlane_b32 s8, v237, 4
	v_readlane_b32 s9, v237, 5
	v_readlane_b32 s10, v237, 6
	v_readlane_b32 s11, v237, 7
	s_mov_b64 s[4:5], s[8:9]
	s_mov_b64 s[6:7], s[10:11]
	s_add_u32 s0, s6, 0x2000
	s_addc_u32 s1, s7, 0
	v_writelane_b32 v237, s0, 54
	s_cmp_lt_i32 s70, 0x8080
	v_mbcnt_lo_u32_b32 v180, -1, 0
	v_writelane_b32 v237, s1, 55
	s_cselect_b64 s[0:1], -1, 0
	v_writelane_b32 v237, s0, 56
	s_cmp_gt_i32 s70, 0x807f
	s_nop 0
	v_writelane_b32 v237, s1, 57
	s_cbranch_scc1 .LBB0_49
	v_readlane_b32 s0, v237, 54
	v_mov_b32_e32 v3, 0
	v_lshlrev_b32_e32 v2, 3, v152
	v_readlane_b32 s1, v237, 55
	v_readlane_b32 s4, v237, 14
	v_readlane_b32 s8, v237, 18
	v_lshl_add_u64 v[34:35], s[0:1], 0, v[2:3]
	v_lshlrev_b32_e32 v2, 4, v152
	v_readlane_b32 s9, v237, 19
	v_readlane_b32 s10, v237, 20
	v_readlane_b32 s11, v237, 21
	v_lshl_add_u64 v[36:37], s[8:9], 0, v[2:3]
	v_mbcnt_hi_u32_b32 v2, -1, v180
	v_and_b32_e32 v1, 64, v2
	v_add_u32_e32 v3, 64, v1
	v_xor_b32_e32 v1, 1, v2
	v_cmp_lt_i32_e32 vcc, v1, v3
	v_xor_b32_e32 v4, 2, v2
	v_readlane_b32 s8, v237, 8
	v_cndmask_b32_e32 v1, v2, v1, vcc
	v_cmp_lt_i32_e32 vcc, v4, v3
	v_readlane_b32 s5, v237, 15
	v_readlane_b32 s6, v237, 16
	v_cndmask_b32_e32 v4, v2, v4, vcc
	v_lshlrev_b32_e32 v38, 2, v4
	v_xor_b32_e32 v4, 4, v2
	v_cmp_lt_i32_e32 vcc, v4, v3
	v_readlane_b32 s14, v237, 24
	v_readlane_b32 s15, v237, 25
	v_cndmask_b32_e32 v4, v2, v4, vcc
	v_lshlrev_b32_e32 v39, 2, v4
	v_xor_b32_e32 v4, 8, v2
	v_cmp_lt_i32_e32 vcc, v4, v3
	v_readlane_b32 s10, v237, 10
	s_mov_b32 s5, 0
	v_cndmask_b32_e32 v4, v2, v4, vcc
	v_lshlrev_b32_e32 v40, 2, v4
	v_xor_b32_e32 v4, 16, v2
	v_cmp_lt_i32_e32 vcc, v4, v3
	v_lshlrev_b32_e32 v1, 2, v1
	s_lshl_b32 s14, s10, 4
	v_cndmask_b32_e32 v4, v2, v4, vcc
	v_lshlrev_b32_e32 v41, 2, v4
	v_xor_b32_e32 v4, 32, v2
	v_cmp_lt_i32_e32 vcc, v4, v3
	v_lshlrev_b32_e32 v43, 4, v152
	v_mov_b32_e32 v44, 0x358637bd
	v_cndmask_b32_e32 v2, v2, v4, vcc
	v_lshlrev_b32_e32 v42, 2, v2
	s_mov_b32 s15, 0xf800000
	v_mov_b32_e32 v45, 0x260
	s_mov_b32 s6, s70
	v_readlane_b32 s7, v237, 17
	v_readlane_b32 s12, v237, 22
	v_readlane_b32 s13, v237, 23
	v_readlane_b32 s16, v237, 26
	v_readlane_b32 s17, v237, 27
	v_readlane_b32 s18, v237, 28
	v_readlane_b32 s19, v237, 29
	v_readlane_b32 s9, v237, 9
	v_readlane_b32 s11, v237, 11
	global_load_dwordx4 v[64:67], v[36:37], off
	global_load_dwordx4 v[68:71], v[36:37], off offset:1024
	global_load_dwordx4 v[72:75], v[36:37], off offset:2048
	global_load_dwordx4 v[76:79], v[36:37], off offset:3072
	s_waitcnt vmcnt(0)
	s_branch .LBB0_39

; __device__ __forceinline__ void rms_store_bf16(const f32x4 (&v)[4], const float* g, bf16_t* orow, int lane) {
;     float s = 0.f;
; #pragma unroll
;     for (int j = 0; j < 4; ++j) s += (v[j].x * v[j].x + v[j].y * v[j].y) + (v[j].z * v[j].z + v[j].w * v[j].w);
;     const float rs = 1.f / sqrtf(wave_sum(s) * (1.f / 1024.f) + EPS);
;     unsigned long long* o8 = (unsigned long long*)orow + lane;
; #pragma unroll
;     for (int j = 0; j < 4; ++j) { const f32x4 gg = *((const f32x4*)g + lane + 64 * j);
;         o8[64 * j] = (unsigned long long)pk2(v[j].x * rs * gg.x, v[j].y * rs * gg.y) | ((unsigned long long)pk2(v[j].z * rs * gg.z, v[j].w * rs * gg.w) << 32); }
; }
.LBB0_47:
	s_waitcnt vmcnt(3)
	v_pk_mul_f32 v[6:7], v[28:29], v[28:29]
	v_pk_mul_f32 v[8:9], v[26:27], v[26:27]
	global_load_dwordx4 v[30:33], v43, s[0:1] nt
	global_load_dwordx4 v[22:25], v43, s[0:1] offset:1024 nt
	v_pk_mov_b32 v[14:15], v[8:9], v[6:7] op_sel:[1,0]
	v_mov_b32_e32 v9, v7
	v_pk_add_f32 v[6:7], v[14:15], v[8:9]
	s_waitcnt vmcnt(4)
	v_pk_mul_f32 v[8:9], v[20:21], v[20:21]
	v_pk_mul_f32 v[14:15], v[18:19], v[18:19]
	v_pk_add_f32 v[6:7], v[6:7], v[6:7] op_sel:[0,1] op_sel_hi:[1,0]
	v_pk_mov_b32 v[16:17], v[14:15], v[8:9] op_sel:[1,0]
	v_mov_b32_e32 v15, v9
	v_pk_add_f32 v[8:9], v[16:17], v[14:15]
	s_waitcnt vmcnt(2)
	v_mul_f32_e32 v14, v2, v2
	v_mul_f32_e32 v15, v3, v3
	v_pk_add_f32 v[8:9], v[8:9], v[8:9] op_sel:[0,1] op_sel_hi:[1,0]
	v_mov_b32_e32 v7, v14
	v_mov_b32_e32 v9, v15
	v_pk_add_f32 v[6:7], v[6:7], v[8:9]
	v_mul_f32_e32 v8, v11, v11
	v_mul_f32_e32 v14, v13, v13
	v_mul_f32_e32 v16, v4, v4
	v_mul_f32_e32 v17, v5, v5
	v_pk_fma_f32 v[8:9], v[10:11], v[10:11], v[8:9] op_sel_hi:[1,1,0]
	v_pk_fma_f32 v[14:15], v[12:13], v[12:13], v[14:15] op_sel_hi:[1,1,0]
	v_mov_b32_e32 v9, v16
	v_mov_b32_e32 v15, v17
	v_pk_add_f32 v[8:9], v[8:9], v[14:15]
	s_ashr_i32 s7, s6, 31
	v_pk_add_f32 v[6:7], v[6:7], v[8:9]
	s_lshl_b64 s[10:11], s[6:7], 11
	v_add_f32_e32 v6, v6, v7
	ds_bpermute_b32 v7, v1, v6
	s_cmp_gt_i32 s8, 0x807f
	s_waitcnt lgkmcnt(0)
	v_add_f32_e32 v6, v6, v7
	ds_bpermute_b32 v7, v38, v6
	s_waitcnt lgkmcnt(0)
	v_add_f32_e32 v6, v6, v7
	ds_bpermute_b32 v7, v39, v6
	s_waitcnt lgkmcnt(0)
	v_add_f32_e32 v6, v6, v7
	ds_bpermute_b32 v7, v40, v6
	s_waitcnt lgkmcnt(0)
	v_add_f32_e32 v6, v6, v7
	ds_bpermute_b32 v7, v41, v6
	s_waitcnt lgkmcnt(0)
	v_add_f32_e32 v6, v6, v7
	ds_bpermute_b32 v7, v42, v6
	s_waitcnt lgkmcnt(0)
	v_add_f32_e32 v6, v6, v7
	v_fmamk_f32 v6, v6, 0x3a800000, v44
	v_mul_f32_e32 v7, 0x4f800000, v6
	v_cmp_gt_f32_e32 vcc, s15, v6
	s_nop 1
	v_cndmask_b32_e32 v50, v6, v7, vcc
	v_sqrt_f32_e32 v51, v50
	global_load_dwordx4 v[14:17], v43, s[0:1] offset:2048 nt
	global_load_dwordx4 v[6:9], v43, s[0:1] offset:3072 nt
	v_add_u32_e32 v52, -1, v51
	v_add_u32_e32 v53, 1, v51
	v_fma_f32 v54, -v52, v51, v50
	v_fma_f32 v55, -v53, v51, v50
	v_cmp_ge_f32_e64 s[0:1], 0, v54
	s_nop 1
	v_cndmask_b32_e64 v51, v51, v52, s[0:1]
	v_cmp_lt_f32_e64 s[0:1], 0, v55
	s_nop 1
	v_cndmask_b32_e64 v51, v51, v53, s[0:1]
	v_mul_f32_e32 v52, 0x37800000, v51
	v_cndmask_b32_e32 v51, v51, v52, vcc
	v_cmp_class_f32_e32 vcc, v50, v45
	s_nop 1
	v_cndmask_b32_e32 v52, v51, v50, vcc
	v_div_scale_f32 v53, s[0:1], v52, v52, 1.0
	v_rcp_f32_e32 v54, v53
	v_div_scale_f32 v55, vcc, 1.0, v52, 1.0
	v_lshl_add_u64 v[50:51], v[34:35], 0, s[10:11]
	v_fma_f32 v56, -v53, v54, 1.0
	v_fmac_f32_e32 v54, v56, v54
	v_mul_f32_e32 v56, v55, v54
	v_fma_f32 v57, -v53, v56, v55
	v_fmac_f32_e32 v56, v57, v54
	v_fma_f32 v53, -v53, v56, v55
	v_div_fmas_f32 v53, v53, v54, v56
	v_div_fixup_f32 v52, v53, v52, 1.0
	v_pk_mul_f32 v[26:27], v[26:27], v[52:53] op_sel_hi:[1,0]
	v_pk_mul_f32 v[28:29], v[28:29], v[52:53] op_sel_hi:[1,0]
	s_waitcnt vmcnt(4)
	v_pk_mul_f32 v[26:27], v[64:65], v[26:27]
	v_pk_mul_f32 v[28:29], v[66:67], v[28:29]
	v_cvt_pk_bf16_f32 v26, v26, v27
	v_cvt_pk_bf16_f32 v27, v28, v29
	global_store_dwordx2 v[50:51], v[26:27], off
	v_pk_mul_f32 v[18:19], v[18:19], v[52:53] op_sel_hi:[1,0]
	v_pk_mul_f32 v[20:21], v[20:21], v[52:53] op_sel_hi:[1,0]
	v_pk_mul_f32 v[10:11], v[10:11], v[52:53] op_sel_hi:[1,0]
	v_pk_mul_f32 v[12:13], v[12:13], v[52:53] op_sel_hi:[1,0]
	v_pk_mul_f32 v[2:3], v[2:3], v[52:53] op_sel_hi:[1,0]
	v_pk_mul_f32 v[4:5], v[4:5], v[52:53] op_sel_hi:[1,0]
	v_pk_mul_f32 v[18:19], v[68:69], v[18:19]
	v_pk_mul_f32 v[20:21], v[70:71], v[20:21]
	v_cvt_pk_bf16_f32 v18, v18, v19
	v_cvt_pk_bf16_f32 v19, v20, v21
	global_store_dwordx2 v[50:51], v[18:19], off offset:512
	v_pk_mul_f32 v[10:11], v[72:73], v[10:11]
	v_pk_mul_f32 v[12:13], v[74:75], v[12:13]
	v_cvt_pk_bf16_f32 v10, v10, v11
	v_cvt_pk_bf16_f32 v11, v12, v13
	global_store_dwordx2 v[50:51], v[10:11], off offset:1024
	v_pk_mul_f32 v[2:3], v[76:77], v[2:3]
	v_pk_mul_f32 v[4:5], v[78:79], v[4:5]
	v_cvt_pk_bf16_f32 v2, v2, v3
	v_cvt_pk_bf16_f32 v3, v4, v5
	global_store_dwordx2 v[50:51], v[2:3], off offset:1536
	s_cbranch_scc1 .LBB0_38
; __device__ __forceinline__ void rms_store_bf16(const f32x4 (&v)[4], const float* g, bf16_t* orow, int lane) {
;     float s = 0.f;
; #pragma unroll
;     for (int j = 0; j < 4; ++j) s += (v[j].x * v[j].x + v[j].y * v[j].y) + (v[j].z * v[j].z + v[j].w * v[j].w);
;     const float rs = 1.f / sqrtf(wave_sum(s) * (1.f / 1024.f) + EPS);
;     unsigned long long* o8 = (unsigned long long*)orow + lane;
; #pragma unroll
;     for (int j = 0; j < 4; ++j) { const f32x4 gg = *((const f32x4*)g + lane + 64 * j);
;         o8[64 * j] = (unsigned long long)pk2(v[j].x * rs * gg.x, v[j].y * rs * gg.y) | ((unsigned long long)pk2(v[j].z * rs * gg.z, v[j].w * rs * gg.w) << 32); }
; }
; __global__ void __launch_bounds__(NTHR, 2) hymba_fwd(Params P) {
;     ...
;             for (int u = 0; u < 2; ++u) { const int t = tt[u];
;                 if (t < TT) rms_store_bf16(v[u], P.mix_pre_g, XN + (size_t)t * 1024, lane); }
	s_waitcnt vmcnt(4)
	v_pk_mul_f32 v[2:3], v[32:33], v[32:33]
	v_pk_mul_f32 v[4:5], v[30:31], v[30:31]
	v_mul_f32_e32 v18, v8, v8
	v_pk_mov_b32 v[10:11], v[4:5], v[2:3] op_sel:[1,0]
	v_mov_b32_e32 v5, v3
	v_pk_add_f32 v[2:3], v[10:11], v[4:5]
	v_pk_mul_f32 v[4:5], v[24:25], v[24:25]
	v_pk_mul_f32 v[10:11], v[22:23], v[22:23]
	v_pk_add_f32 v[2:3], v[2:3], v[2:3] op_sel:[0,1] op_sel_hi:[1,0]
	v_pk_mov_b32 v[12:13], v[10:11], v[4:5] op_sel:[1,0]
	v_mov_b32_e32 v11, v5
	v_pk_add_f32 v[4:5], v[12:13], v[10:11]
	v_mul_f32_e32 v10, v6, v6
	v_mul_f32_e32 v11, v7, v7
	v_pk_add_f32 v[4:5], v[4:5], v[4:5] op_sel:[0,1] op_sel_hi:[1,0]
	v_mov_b32_e32 v3, v10
	v_mov_b32_e32 v5, v11
	v_pk_add_f32 v[10:11], v[2:3], v[4:5]
	v_mul_f32_e32 v2, v15, v15
	v_pk_fma_f32 v[12:13], v[14:15], v[14:15], v[2:3] op_sel_hi:[1,1,0]
	v_mov_b32_e32 v13, v18
	v_mul_f32_e32 v18, v17, v17
	v_mul_f32_e32 v20, v9, v9
	v_pk_fma_f32 v[18:19], v[16:17], v[16:17], v[18:19] op_sel_hi:[1,1,0]
	s_ashr_i32 s9, s8, 31
	v_mov_b32_e32 v19, v20
	v_pk_add_f32 v[12:13], v[12:13], v[18:19]
	s_lshl_b64 s[8:9], s[8:9], 11
	v_pk_add_f32 v[10:11], v[10:11], v[12:13]
	s_nop 0
	v_add_f32_e32 v10, v10, v11
	ds_bpermute_b32 v11, v1, v10
	s_waitcnt lgkmcnt(0)
	v_add_f32_e32 v10, v10, v11
	ds_bpermute_b32 v11, v38, v10
	s_waitcnt lgkmcnt(0)
	v_add_f32_e32 v10, v10, v11
	ds_bpermute_b32 v11, v39, v10
	s_waitcnt lgkmcnt(0)
	v_add_f32_e32 v10, v10, v11
	ds_bpermute_b32 v11, v40, v10
	s_waitcnt lgkmcnt(0)
	v_add_f32_e32 v10, v10, v11
	ds_bpermute_b32 v11, v41, v10
	s_waitcnt lgkmcnt(0)
	v_add_f32_e32 v10, v10, v11
	ds_bpermute_b32 v11, v42, v10
	s_waitcnt lgkmcnt(0)
	v_add_f32_e32 v10, v10, v11
	v_fmamk_f32 v10, v10, 0x3a800000, v44
	v_mul_f32_e32 v11, 0x4f800000, v10
	v_cmp_gt_f32_e32 vcc, s15, v10
	s_nop 1
	v_cndmask_b32_e32 v10, v10, v11, vcc
	v_sqrt_f32_e32 v11, v10
	s_nop 0
	v_add_u32_e32 v12, -1, v11
	v_add_u32_e32 v13, 1, v11
	v_fma_f32 v18, -v12, v11, v10
	v_fma_f32 v19, -v13, v11, v10
	v_cmp_ge_f32_e64 s[0:1], 0, v18
	s_nop 1
	v_cndmask_b32_e64 v11, v11, v12, s[0:1]
	v_cmp_lt_f32_e64 s[0:1], 0, v19
	s_nop 1
	v_cndmask_b32_e64 v11, v11, v13, s[0:1]
	v_mul_f32_e32 v12, 0x37800000, v11
	v_cndmask_b32_e32 v11, v11, v12, vcc
	v_cmp_class_f32_e32 vcc, v10, v45
	s_nop 1
	v_cndmask_b32_e32 v12, v11, v10, vcc
	v_div_scale_f32 v13, s[0:1], v12, v12, 1.0
	v_rcp_f32_e32 v18, v13
	v_div_scale_f32 v19, vcc, 1.0, v12, 1.0
	v_lshl_add_u64 v[10:11], v[34:35], 0, s[8:9]
	v_fma_f32 v20, -v13, v18, 1.0
	v_fmac_f32_e32 v18, v20, v18
	v_mul_f32_e32 v20, v19, v18
	v_fma_f32 v21, -v13, v20, v19
	v_fmac_f32_e32 v20, v21, v18
	v_fma_f32 v13, -v13, v20, v19
	v_div_fmas_f32 v13, v13, v18, v20
	v_div_fixup_f32 v12, v13, v12, 1.0
	v_pk_mul_f32 v[18:19], v[30:31], v[12:13] op_sel_hi:[1,0]
	v_pk_mul_f32 v[20:21], v[32:33], v[12:13] op_sel_hi:[1,0]
	v_pk_mul_f32 v[2:3], v[64:65], v[18:19]
	v_pk_mul_f32 v[4:5], v[66:67], v[20:21]
	v_cvt_pk_bf16_f32 v2, v2, v3
	v_cvt_pk_bf16_f32 v3, v4, v5
	global_store_dwordx2 v[10:11], v[2:3], off
	v_pk_mul_f32 v[18:19], v[22:23], v[12:13] op_sel_hi:[1,0]
	v_pk_mul_f32 v[20:21], v[24:25], v[12:13] op_sel_hi:[1,0]
	v_pk_mul_f32 v[14:15], v[14:15], v[12:13] op_sel_hi:[1,0]
	v_pk_mul_f32 v[16:17], v[16:17], v[12:13] op_sel_hi:[1,0]
	v_pk_mul_f32 v[6:7], v[6:7], v[12:13] op_sel_hi:[1,0]
	v_pk_mul_f32 v[8:9], v[8:9], v[12:13] op_sel_hi:[1,0]
	v_pk_mul_f32 v[2:3], v[68:69], v[18:19]
	v_pk_mul_f32 v[4:5], v[70:71], v[20:21]
	v_cvt_pk_bf16_f32 v2, v2, v3
	v_cvt_pk_bf16_f32 v3, v4, v5
	global_store_dwordx2 v[10:11], v[2:3], off offset:512
	v_pk_mul_f32 v[2:3], v[72:73], v[14:15]
	v_pk_mul_f32 v[4:5], v[74:75], v[16:17]
	v_cvt_pk_bf16_f32 v2, v2, v3
	v_cvt_pk_bf16_f32 v3, v4, v5
	global_store_dwordx2 v[10:11], v[2:3], off offset:1024
	v_pk_mul_f32 v[2:3], v[76:77], v[6:7]
	v_pk_mul_f32 v[4:5], v[78:79], v[8:9]
	v_cvt_pk_bf16_f32 v2, v2, v3
	v_cvt_pk_bf16_f32 v3, v4, v5
	global_store_dwordx2 v[10:11], v[2:3], off offset:1536
	s_branch .LBB0_38

; __global__ void __launch_bounds__(NTHR, 2) hymba_fwd(Params P) {
;     ...
;         for (int t0 = gw; t0 < TT; t0 += 4 * NGW) {
;             u32x4 q[4][2][2]; int tt[4];
; #pragma unroll
;             for (int u = 0; u < 4; ++u) { const int t = t0 + u * NGW; tt[u] = t; const int tc = t < TT ? t : TT - 1;
; #pragma unroll
;                 for (int half = 0; half < 2; ++half) { const bf16_t* src = (half ? OSB : YSSD) + (size_t)tc * 1024;
; #pragma unroll
;                     for (int j = 0; j < 2; ++j) q[u][half][j] = __builtin_nontemporal_load((const u32x4*)src + lane + 64 * j); } }
; #pragma unroll
;             for (int u = 0; u < 4; ++u) { const int t = tt[u]; if (t >= TT) continue;
;                 bf16_t* orow = MIXIN + (size_t)t * MIXW;
; #pragma unroll
;                 for (int half = 0; half < 2; ++half) {
;                     const float* gg = half ? P.sb_norm_g : P.ssd_norm_g;
;                     float v[16]; float s = 0.f;
; #pragma unroll
;                     for (int j = 0; j < 2; ++j) { const u32x4 qq = q[u][half][j];
;                         v[8 * j + 0] = bflo(qq.x); v[8 * j + 1] = bfhi(qq.x); v[8 * j + 2] = bflo(qq.y); v[8 * j + 3] = bfhi(qq.y); v[8 * j + 4] = bflo(qq.z); v[8 * j + 5] = bfhi(qq.z); v[8 * j + 6] = bflo(qq.w); v[8 * j + 7] = bfhi(qq.w); }
; #pragma unroll
;                     for (int j = 0; j < 16; ++j) s += v[j] * v[j];
;                     const float rs = 1.f / sqrtf(wave_sum(s) * (1.f / 1024.f) + EPS);
; #pragma unroll
;                     for (int j = 0; j < 2; ++j) { const f32x4 ga = *(const f32x4*)(gg + 8 * lane + 512 * j), gb = *(const f32x4*)(gg + 8 * lane + 512 * j + 4); u32x4 w;
.LBB0_619:
	s_or_b64 exec, exec, s[0:1]
	v_readlane_b32 s0, v237, 56
	v_readlane_b32 s1, v237, 57
	s_andn2_b64 vcc, exec, s[0:1]
	s_waitcnt lgkmcnt(0)
	v_cndmask_b32_e64 v0, 0, 1, s[0:1]
	v_cmp_ne_u32_e64 s[4:5], 1, v0
	s_barrier
	s_cbranch_vccnz .LBB0_628
	v_ashrrev_i32_e32 v153, 31, v152
	v_readlane_b32 s8, v237, 0
	v_lshlrev_b64 v[2:3], 4, v[152:153]
	v_readlane_b32 s14, v237, 6
	v_readlane_b32 s15, v237, 7
	v_lshl_add_u64 v[48:49], s[50:51], 0, v[2:3]
	v_lshl_add_u64 v[50:51], s[54:55], 0, v[2:3]
	v_lshl_add_u64 v[52:53], s[14:15], 0, v[2:3]
	v_mbcnt_hi_u32_b32 v2, -1, v180
	v_and_b32_e32 v3, 64, v2
	v_add_u32_e32 v3, 64, v3
	v_xor_b32_e32 v4, 1, v2
	v_cmp_lt_i32_e32 vcc, v4, v3
	v_readlane_b32 s9, v237, 1
	v_readlane_b32 s10, v237, 2
	v_cndmask_b32_e32 v4, v2, v4, vcc
	v_lshlrev_b32_e32 v62, 2, v4
	v_xor_b32_e32 v4, 2, v2
	v_cmp_lt_i32_e32 vcc, v4, v3
	v_readlane_b32 s11, v237, 3
	v_readlane_b32 s12, v237, 4
	v_cndmask_b32_e32 v4, v2, v4, vcc
	v_lshlrev_b32_e32 v63, 2, v4
	v_xor_b32_e32 v4, 4, v2
	v_cmp_lt_i32_e32 vcc, v4, v3
	v_readlane_b32 s13, v237, 5
	v_lshlrev_b32_e32 v0, 3, v152
	v_cndmask_b32_e32 v4, v2, v4, vcc
	v_lshlrev_b32_e32 v64, 2, v4
	v_xor_b32_e32 v4, 8, v2
	v_cmp_lt_i32_e32 vcc, v4, v3
	v_readlane_b32 s8, v237, 30
	v_ashrrev_i32_e32 v1, 31, v0
	v_cndmask_b32_e32 v4, v2, v4, vcc
	v_lshlrev_b32_e32 v65, 2, v4
	v_xor_b32_e32 v4, 16, v2
	v_cmp_lt_i32_e32 vcc, v4, v3
	v_readlane_b32 s9, v237, 31
	v_readlane_b32 s10, v237, 32
	v_cndmask_b32_e32 v4, v2, v4, vcc
	v_lshlrev_b32_e32 v66, 2, v4
	v_xor_b32_e32 v4, 32, v2
	v_cmp_lt_i32_e32 vcc, v4, v3
	v_readlane_b32 s11, v237, 33
	v_readlane_b32 s12, v237, 34
	v_readlane_b32 s13, v237, 35
	v_readlane_b32 s0, v237, 8
	v_cndmask_b32_e32 v2, v2, v4, vcc
	v_lshlrev_b64 v[0:1], 2, v[0:1]
	v_readlane_b32 s14, v237, 36
	v_readlane_b32 s15, v237, 37
	s_mov_b64 s[6:7], s[10:11]
	s_mov_b64 s[8:9], s[12:13]
	v_readlane_b32 s2, v237, 10
	v_lshlrev_b32_e32 v67, 2, v2
	v_lshl_add_u64 v[54:55], s[6:7], 0, v[0:1]
	v_lshl_add_u64 v[56:57], s[8:9], 0, v[0:1]
	s_lshl_b32 s12, s2, 5
	s_lshl_b32 s13, s2, 4
	s_mul_i32 s14, s2, 24
	v_mov_b32_e32 v68, 0x358637bd
	s_mov_b32 s15, 0xf800000
	v_mov_b32_e32 v69, 0x260
	s_mov_b32 s2, s70
	v_readlane_b32 s16, v237, 38
	v_readlane_b32 s17, v237, 39
	v_readlane_b32 s18, v237, 40
	v_readlane_b32 s19, v237, 41
	v_readlane_b32 s20, v237, 42
	v_readlane_b32 s21, v237, 43
	v_readlane_b32 s22, v237, 44
	v_readlane_b32 s23, v237, 45
	v_readlane_b32 s1, v237, 9
	v_readlane_b32 s3, v237, 11
	global_load_dwordx4 v[120:123], v[54:55], off
	global_load_dwordx4 v[124:127], v[54:55], off offset:16
	global_load_dwordx4 v[128:131], v[54:55], off offset:2048
	global_load_dwordx4 v[132:135], v[54:55], off offset:2064
	global_load_dwordx4 v[136:139], v[56:57], off
	global_load_dwordx4 v[140:143], v[56:57], off offset:16
	global_load_dwordx4 v[144:147], v[56:57], off offset:2048
	global_load_dwordx4 v[148:151], v[56:57], off offset:2064
	s_waitcnt vmcnt(0)
	s_branch .LBB0_622

; __global__ void __launch_bounds__(NTHR, 2) hymba_fwd(Params P) {
;     ...
;             for (int u = 0; u < 4; ++u) { const int t = t0 + u * NGW; tt[u] = t; const int tc = t < TT ? t : TT - 1;
; #pragma unroll
;                 for (int half = 0; half < 2; ++half) { const bf16_t* src = (half ? OSB : YSSD) + (size_t)tc * 1024;
; #pragma unroll
;                     for (int j = 0; j < 2; ++j) q[u][half][j] = __builtin_nontemporal_load((const u32x4*)src + lane + 64 * j); } }
; #pragma unroll
;             for (int u = 0; u < 4; ++u) { const int t = tt[u]; if (t >= TT) continue;
;                 bf16_t* orow = MIXIN + (size_t)t * MIXW;
; #pragma unroll
;                 for (int half = 0; half < 2; ++half) {
;                     const float* gg = half ? P.sb_norm_g : P.ssd_norm_g;
;                     float v[16]; float s = 0.f;
; #pragma unroll
;                     for (int j = 0; j < 2; ++j) { const u32x4 qq = q[u][half][j];
;                         v[8 * j + 0] = bflo(qq.x); v[8 * j + 1] = bfhi(qq.x); v[8 * j + 2] = bflo(qq.y); v[8 * j + 3] = bfhi(qq.y); v[8 * j + 4] = bflo(qq.z); v[8 * j + 5] = bfhi(qq.z); v[8 * j + 6] = bflo(qq.w); v[8 * j + 7] = bfhi(qq.w); }
; #pragma unroll
;                     for (int j = 0; j < 16; ++j) s += v[j] * v[j];
;                     const float rs = 1.f / sqrtf(wave_sum(s) * (1.f / 1024.f) + EPS);
; #pragma unroll
;                     for (int j = 0; j < 2; ++j) { const f32x4 ga = *(const f32x4*)(gg + 8 * lane + 512 * j), gb = *(const f32x4*)(gg + 8 * lane + 512 * j + 4); u32x4 w;
;                         w.x = pk2(v[8 * j + 0] * rs * ga.x, v[8 * j + 1] * rs * ga.y); w.y = pk2(v[8 * j + 2] * rs * ga.z, v[8 * j + 3] * rs * ga.w);
;                         w.z = pk2(v[8 * j + 4] * rs * gb.x, v[8 * j + 5] * rs * gb.y); w.w = pk2(v[8 * j + 6] * rs * gb.z, v[8 * j + 7] * rs * gb.w);
;                         *((u32x4*)(orow + half * 1024) + lane + 64 * j) = w; }
.LBB0_622:
	s_ashr_i32 s3, s2, 31
	s_lshl_b64 s[0:1], s[2:3], 11
	v_lshl_add_u64 v[4:5], v[50:51], 0, s[0:1]
	global_load_dwordx4 v[0:3], v[4:5], off offset:1024 nt
	s_nop 0
	global_load_dwordx4 v[4:7], v[4:5], off nt
	s_nop 0
	s_add_i32 s10, s89, s2
	s_min_i32 s16, s10, 0x807f
	s_ashr_i32 s17, s16, 31
	s_add_i32 s8, s13, s2
	s_min_i32 s18, s8, 0x807f
	s_ashr_i32 s19, s18, 31
	s_add_i32 s6, s14, s2
	s_min_i32 s20, s6, 0x807f
	s_ashr_i32 s21, s20, 31
	s_lshl_b64 s[22:23], s[2:3], 12
	v_lshl_add_u64 v[58:59], v[48:49], 0, s[22:23]
	s_waitcnt vmcnt(1)
	v_lshlrev_b32_e32 v60, 16, v3
	s_waitcnt vmcnt(0)
	v_lshlrev_b32_e32 v92, 16, v4
	v_and_b32_e32 v93, 0xffff0000, v4
	v_lshlrev_b32_e32 v90, 16, v5
	v_and_b32_e32 v91, 0xffff0000, v5
	v_pk_mul_f32 v[8:9], v[92:93], v[92:93]
	v_lshlrev_b32_e32 v86, 16, v7
	v_and_b32_e32 v87, 0xffff0000, v7
	v_lshlrev_b32_e32 v88, 16, v6
	v_and_b32_e32 v89, 0xffff0000, v6
	v_pk_mul_f32 v[6:7], v[90:91], v[90:91]
	v_add_f32_e32 v8, v8, v9
	v_add_f32_e32 v6, v8, v6
	v_pk_mul_f32 v[4:5], v[88:89], v[88:89]
	v_add_f32_e32 v6, v6, v7
	v_add_f32_e32 v4, v6, v4
	v_and_b32_e32 v61, 0xffff0000, v3
	v_lshlrev_b32_e32 v94, 16, v2
	v_and_b32_e32 v95, 0xffff0000, v2
	v_pk_mul_f32 v[2:3], v[86:87], v[86:87]
	v_add_f32_e32 v4, v4, v5
	v_lshlrev_b32_e32 v98, 16, v0
	v_and_b32_e32 v99, 0xffff0000, v0
	v_add_f32_e32 v2, v4, v2
	v_pk_mul_f32 v[14:15], v[98:99], v[98:99]
	v_add_f32_e32 v2, v2, v3
	v_lshlrev_b32_e32 v96, 16, v1
	v_and_b32_e32 v97, 0xffff0000, v1
	v_add_f32_e32 v2, v2, v14
	v_pk_mul_f32 v[12:13], v[96:97], v[96:97]
	v_add_f32_e32 v2, v2, v15
	v_add_f32_e32 v2, v2, v12
	v_pk_mul_f32 v[10:11], v[94:95], v[94:95]
	v_add_f32_e32 v2, v2, v13
	v_add_f32_e32 v2, v2, v10
	v_pk_mul_f32 v[0:1], v[60:61], v[60:61]
	v_add_f32_e32 v2, v2, v11
	v_add_f32_e32 v0, v2, v0
	v_add_f32_e32 v0, v0, v1
	ds_bpermute_b32 v1, v62, v0
	s_waitcnt lgkmcnt(0)
	v_add_f32_e32 v2, v0, v1
	ds_bpermute_b32 v3, v63, v2
	v_lshl_add_u64 v[0:1], v[52:53], 0, s[0:1]
	s_lshl_b64 s[0:1], s[16:17], 11
	global_load_dwordx4 v[78:81], v[0:1], off offset:1024 nt
	global_load_dwordx4 v[82:85], v[0:1], off nt
	v_lshl_add_u64 v[0:1], v[50:51], 0, s[0:1]
	s_waitcnt lgkmcnt(0)
	v_add_f32_e32 v2, v2, v3
	ds_bpermute_b32 v3, v64, v2
	global_load_dwordx4 v[44:47], v[0:1], off nt
	global_load_dwordx4 v[40:43], v[0:1], off offset:1024 nt
	s_lshl_b64 s[16:17], s[18:19], 11
	v_lshl_add_u64 v[4:5], v[50:51], 0, s[16:17]
	s_lshl_b64 s[18:19], s[20:21], 11
	s_waitcnt lgkmcnt(0)
	v_add_f32_e32 v8, v2, v3
	ds_bpermute_b32 v9, v65, v8
	v_lshl_add_u64 v[2:3], v[52:53], 0, s[0:1]
	global_load_dwordx4 v[36:39], v[2:3], off nt
	global_load_dwordx4 v[32:35], v[2:3], off offset:1024 nt
	global_load_dwordx4 v[28:31], v[4:5], off nt
	global_load_dwordx4 v[24:27], v[4:5], off offset:1024 nt
	v_lshl_add_u64 v[6:7], v[52:53], 0, s[16:17]
	v_lshl_add_u64 v[100:101], v[52:53], 0, s[18:19]
	s_waitcnt lgkmcnt(0)
	v_add_f32_e32 v10, v8, v9
	ds_bpermute_b32 v11, v66, v10
	v_lshl_add_u64 v[8:9], v[50:51], 0, s[18:19]
	s_cmp_gt_i32 s10, 0x807f
	s_waitcnt lgkmcnt(0)
	v_add_f32_e32 v0, v10, v11
	ds_bpermute_b32 v1, v67, v0
	global_load_dwordx4 v[20:23], v[6:7], off nt
	global_load_dwordx4 v[16:19], v[6:7], off offset:1024 nt
	global_load_dwordx4 v[12:15], v[8:9], off nt
	s_nop 0
	global_load_dwordx4 v[8:11], v[8:9], off offset:1024 nt
	s_waitcnt lgkmcnt(0)
	v_add_f32_e32 v0, v0, v1
	v_fmamk_f32 v0, v0, 0x3a800000, v68
	v_mul_f32_e32 v1, 0x4f800000, v0
	v_cmp_gt_f32_e32 vcc, s15, v0
	s_nop 1
	v_cndmask_b32_e32 v0, v0, v1, vcc
	v_sqrt_f32_e32 v1, v0
	s_nop 0
	v_add_u32_e32 v2, -1, v1
	v_add_u32_e32 v3, 1, v1
	v_fma_f32 v4, -v2, v1, v0
	v_fma_f32 v5, -v3, v1, v0
	v_cmp_ge_f32_e64 s[0:1], 0, v4
	s_nop 1
	v_cndmask_b32_e64 v1, v1, v2, s[0:1]
	v_cmp_lt_f32_e64 s[0:1], 0, v5
	s_nop 1
	v_cndmask_b32_e64 v1, v1, v3, s[0:1]
	v_mul_f32_e32 v2, 0x37800000, v1
	v_cndmask_b32_e32 v1, v1, v2, vcc
	v_cmp_class_f32_e32 vcc, v0, v69
	s_nop 1
	v_cndmask_b32_e32 v102, v1, v0, vcc
	v_div_scale_f32 v103, s[0:1], v102, v102, 1.0
	v_rcp_f32_e32 v104, v103
	global_load_dwordx4 v[4:7], v[100:101], off nt
	global_load_dwordx4 v[0:3], v[100:101], off offset:1024 nt
	v_div_scale_f32 v100, vcc, 1.0, v102, 1.0
	v_fma_f32 v101, -v103, v104, 1.0
	v_fmac_f32_e32 v104, v101, v104
	v_mul_f32_e32 v101, v100, v104
	v_fma_f32 v105, -v103, v101, v100
	v_fmac_f32_e32 v101, v105, v104
	v_fma_f32 v100, -v103, v101, v100
	v_div_fmas_f32 v100, v100, v104, v101
	v_div_fixup_f32 v100, v100, v102, 1.0
	v_pk_mul_f32 v[92:93], v[100:101], v[92:93] op_sel_hi:[0,1]
	v_pk_mul_f32 v[90:91], v[100:101], v[90:91] op_sel_hi:[0,1]
	v_pk_mul_f32 v[88:89], v[100:101], v[88:89] op_sel_hi:[0,1]
	v_pk_mul_f32 v[86:87], v[100:101], v[86:87] op_sel_hi:[0,1]
	v_pk_mul_f32 v[74:75], v[92:93], v[120:121]
	v_pk_mul_f32 v[76:77], v[90:91], v[122:123]
	v_pk_mul_f32 v[88:89], v[88:89], v[124:125]
	v_pk_mul_f32 v[86:87], v[86:87], v[126:127]
	v_cvt_pk_bf16_f32 v70, v74, v75
	v_cvt_pk_bf16_f32 v71, v76, v77
	v_cvt_pk_bf16_f32 v72, v88, v89
	v_cvt_pk_bf16_f32 v73, v86, v87
	global_store_dwordx4 v[58:59], v[70:73], off
	s_nop 1
	s_nop 0
	s_waitcnt vmcnt(13)
; __global__ void __launch_bounds__(NTHR, 2) hymba_fwd(Params P) {
;     ...
;                 for (int half = 0; half < 2; ++half) {
;                     const float* gg = half ? P.sb_norm_g : P.ssd_norm_g;
;                     float v[16]; float s = 0.f;
; #pragma unroll
;                     for (int j = 0; j < 2; ++j) { const u32x4 qq = q[u][half][j];
;                         v[8 * j + 0] = bflo(qq.x); v[8 * j + 1] = bfhi(qq.x); v[8 * j + 2] = bflo(qq.y); v[8 * j + 3] = bfhi(qq.y); v[8 * j + 4] = bflo(qq.z); v[8 * j + 5] = bfhi(qq.z); v[8 * j + 6] = bflo(qq.w); v[8 * j + 7] = bfhi(qq.w); }
; #pragma unroll
;                     for (int j = 0; j < 16; ++j) s += v[j] * v[j];
;                     const float rs = 1.f / sqrtf(wave_sum(s) * (1.f / 1024.f) + EPS);
; #pragma unroll
;                     for (int j = 0; j < 2; ++j) { const f32x4 ga = *(const f32x4*)(gg + 8 * lane + 512 * j), gb = *(const f32x4*)(gg + 8 * lane + 512 * j + 4); u32x4 w;
;                         w.x = pk2(v[8 * j + 0] * rs * ga.x, v[8 * j + 1] * rs * ga.y); w.y = pk2(v[8 * j + 2] * rs * ga.z, v[8 * j + 3] * rs * ga.w);
;                         w.z = pk2(v[8 * j + 4] * rs * gb.x, v[8 * j + 5] * rs * gb.y); w.w = pk2(v[8 * j + 6] * rs * gb.z, v[8 * j + 7] * rs * gb.w);
;                         *((u32x4*)(orow + half * 1024) + lane + 64 * j) = w; }
	v_lshlrev_b32_e32 v92, 16, v82
	v_and_b32_e32 v93, 0xffff0000, v82
	v_lshlrev_b32_e32 v88, 16, v85
	v_and_b32_e32 v89, 0xffff0000, v85
	v_lshlrev_b32_e32 v90, 16, v84
	v_and_b32_e32 v91, 0xffff0000, v84
	v_lshlrev_b32_e32 v84, 16, v83
	v_and_b32_e32 v85, 0xffff0000, v83
	v_pk_mul_f32 v[110:111], v[92:93], v[92:93]
	v_pk_mul_f32 v[108:109], v[84:85], v[84:85]
	v_add_f32_e32 v101, v110, v111
	v_add_f32_e32 v101, v101, v108
	v_pk_mul_f32 v[106:107], v[90:91], v[90:91]
	v_add_f32_e32 v101, v101, v109
	v_add_f32_e32 v101, v101, v106
	v_pk_mul_f32 v[104:105], v[88:89], v[88:89]
	v_add_f32_e32 v101, v101, v107
	v_lshlrev_b32_e32 v102, 16, v78
	v_and_b32_e32 v103, 0xffff0000, v78
	v_add_f32_e32 v101, v101, v104
	v_pk_mul_f32 v[116:117], v[102:103], v[102:103]
	v_add_f32_e32 v101, v101, v105
	v_lshlrev_b32_e32 v86, 16, v81
	v_and_b32_e32 v87, 0xffff0000, v81
	v_lshlrev_b32_e32 v82, 16, v80
	v_and_b32_e32 v83, 0xffff0000, v80
	v_lshlrev_b32_e32 v80, 16, v79
	v_and_b32_e32 v81, 0xffff0000, v79
	v_add_f32_e32 v101, v101, v116
	v_pk_mul_f32 v[114:115], v[80:81], v[80:81]
	v_add_f32_e32 v101, v101, v117
	v_add_f32_e32 v101, v101, v114
	v_add_f32_e32 v101, v101, v115
	v_pk_mul_f32 v[98:99], v[100:101], v[98:99] op_sel_hi:[0,1]
	v_pk_mul_f32 v[96:97], v[100:101], v[96:97] op_sel_hi:[0,1]
	v_pk_mul_f32 v[94:95], v[100:101], v[94:95] op_sel_hi:[0,1]
	v_pk_mul_f32 v[60:61], v[100:101], v[60:61] op_sel_hi:[0,1]
	v_pk_mul_f32 v[112:113], v[82:83], v[82:83]
	v_pk_mul_f32 v[78:79], v[86:87], v[86:87]
	v_pk_mul_f32 v[70:71], v[98:99], v[128:129]
	v_pk_mul_f32 v[72:73], v[96:97], v[130:131]
	v_pk_mul_f32 v[74:75], v[94:95], v[132:133]
	v_pk_mul_f32 v[60:61], v[60:61], v[134:135]
	v_cvt_pk_bf16_f32 v70, v70, v71
	v_cvt_pk_bf16_f32 v71, v72, v73
	v_cvt_pk_bf16_f32 v72, v74, v75
	v_cvt_pk_bf16_f32 v73, v60, v61
	global_store_dwordx4 v[58:59], v[70:73], off offset:1024
	s_nop 1
	s_nop 0
	v_add_f32_e32 v60, v101, v112
	v_add_f32_e32 v60, v60, v113
	v_add_f32_e32 v60, v60, v78
	v_add_f32_e32 v60, v60, v79
	ds_bpermute_b32 v61, v62, v60
	s_waitcnt lgkmcnt(0)
	v_add_f32_e32 v60, v60, v61
	ds_bpermute_b32 v61, v63, v60
	s_waitcnt lgkmcnt(0)
	v_add_f32_e32 v60, v60, v61
	ds_bpermute_b32 v61, v64, v60
	s_waitcnt lgkmcnt(0)
	v_add_f32_e32 v60, v60, v61
	ds_bpermute_b32 v61, v65, v60
	s_waitcnt lgkmcnt(0)
	v_add_f32_e32 v60, v60, v61
	ds_bpermute_b32 v61, v66, v60
	s_waitcnt lgkmcnt(0)
	v_add_f32_e32 v60, v60, v61
	ds_bpermute_b32 v61, v67, v60
	s_waitcnt lgkmcnt(0)
	v_add_f32_e32 v60, v60, v61
	v_fmamk_f32 v60, v60, 0x3a800000, v68
	v_mul_f32_e32 v61, 0x4f800000, v60
	v_cmp_gt_f32_e32 vcc, s15, v60
	s_nop 1
	v_cndmask_b32_e32 v60, v60, v61, vcc
	v_sqrt_f32_e32 v61, v60
	s_nop 0
	v_add_u32_e32 v78, -1, v61
	v_add_u32_e32 v79, 1, v61
	v_fma_f32 v94, -v78, v61, v60
	v_fma_f32 v95, -v79, v61, v60
	v_cmp_ge_f32_e64 s[0:1], 0, v94
	s_nop 1
	v_cndmask_b32_e64 v61, v61, v78, s[0:1]
	v_cmp_lt_f32_e64 s[0:1], 0, v95
	s_nop 1
	v_cndmask_b32_e64 v61, v61, v79, s[0:1]
	v_mul_f32_e32 v78, 0x37800000, v61
	v_cndmask_b32_e32 v61, v61, v78, vcc
	v_cmp_class_f32_e32 vcc, v60, v69
	s_nop 1
	v_cndmask_b32_e32 v60, v61, v60, vcc
	v_div_scale_f32 v61, s[0:1], v60, v60, 1.0
	v_rcp_f32_e32 v78, v61
	v_div_scale_f32 v79, vcc, 1.0, v60, 1.0
	v_fma_f32 v94, -v61, v78, 1.0
	v_fmac_f32_e32 v78, v94, v78
	v_mul_f32_e32 v94, v79, v78
	v_fma_f32 v95, -v61, v94, v79
	v_fmac_f32_e32 v94, v95, v78
	v_fma_f32 v61, -v61, v94, v79
	v_div_fmas_f32 v61, v61, v78, v94
	v_div_fixup_f32 v60, v61, v60, 1.0
	v_pk_mul_f32 v[78:79], v[60:61], v[92:93] op_sel_hi:[0,1]
	v_pk_mul_f32 v[84:85], v[60:61], v[84:85] op_sel_hi:[0,1]
	v_pk_mul_f32 v[90:91], v[60:61], v[90:91] op_sel_hi:[0,1]
	v_pk_mul_f32 v[88:89], v[60:61], v[88:89] op_sel_hi:[0,1]
	v_pk_mul_f32 v[74:75], v[78:79], v[136:137]
	v_pk_mul_f32 v[76:77], v[84:85], v[138:139]
	v_pk_mul_f32 v[78:79], v[90:91], v[140:141]
	v_pk_mul_f32 v[84:85], v[88:89], v[142:143]
	v_cvt_pk_bf16_f32 v70, v74, v75
	v_cvt_pk_bf16_f32 v71, v76, v77
	v_cvt_pk_bf16_f32 v72, v78, v79
	v_cvt_pk_bf16_f32 v73, v84, v85
	global_store_dwordx4 v[58:59], v[70:73], off offset:2048
	s_nop 1
	s_nop 0
	v_pk_mul_f32 v[78:79], v[60:61], v[102:103] op_sel_hi:[0,1]
	v_pk_mul_f32 v[80:81], v[60:61], v[80:81] op_sel_hi:[0,1]
	v_pk_mul_f32 v[82:83], v[60:61], v[82:83] op_sel_hi:[0,1]
	v_pk_mul_f32 v[60:61], v[60:61], v[86:87] op_sel_hi:[0,1]
	v_pk_mul_f32 v[70:71], v[78:79], v[144:145]
	v_pk_mul_f32 v[72:73], v[80:81], v[146:147]
	v_pk_mul_f32 v[74:75], v[82:83], v[148:149]
	v_pk_mul_f32 v[60:61], v[60:61], v[150:151]
	v_cvt_pk_bf16_f32 v70, v70, v71
	v_cvt_pk_bf16_f32 v71, v72, v73
	v_cvt_pk_bf16_f32 v72, v74, v75
	v_cvt_pk_bf16_f32 v73, v60, v61
	global_store_dwordx4 v[58:59], v[70:73], off offset:3072
	s_nop 1
	s_cbranch_scc1 .LBB0_625
; __global__ void __launch_bounds__(NTHR, 2) hymba_fwd(Params P) {
;     ...
;             for (int u = 0; u < 4; ++u) { const int t = tt[u]; if (t >= TT) continue;
;                 bf16_t* orow = MIXIN + (size_t)t * MIXW;
; #pragma unroll
;                 for (int half = 0; half < 2; ++half) {
;                     const float* gg = half ? P.sb_norm_g : P.ssd_norm_g;
;                     float v[16]; float s = 0.f;
; #pragma unroll
;                     for (int j = 0; j < 2; ++j) { const u32x4 qq = q[u][half][j];
;                         v[8 * j + 0] = bflo(qq.x); v[8 * j + 1] = bfhi(qq.x); v[8 * j + 2] = bflo(qq.y); v[8 * j + 3] = bfhi(qq.y); v[8 * j + 4] = bflo(qq.z); v[8 * j + 5] = bfhi(qq.z); v[8 * j + 6] = bflo(qq.w); v[8 * j + 7] = bfhi(qq.w); }
; #pragma unroll
;                     for (int j = 0; j < 16; ++j) s += v[j] * v[j];
;                     const float rs = 1.f / sqrtf(wave_sum(s) * (1.f / 1024.f) + EPS);
; #pragma unroll
;                     for (int j = 0; j < 2; ++j) { const f32x4 ga = *(const f32x4*)(gg + 8 * lane + 512 * j), gb = *(const f32x4*)(gg + 8 * lane + 512 * j + 4); u32x4 w;
;                         w.x = pk2(v[8 * j + 0] * rs * ga.x, v[8 * j + 1] * rs * ga.y); w.y = pk2(v[8 * j + 2] * rs * ga.z, v[8 * j + 3] * rs * ga.w);
;                         w.z = pk2(v[8 * j + 4] * rs * gb.x, v[8 * j + 5] * rs * gb.y); w.w = pk2(v[8 * j + 6] * rs * gb.z, v[8 * j + 7] * rs * gb.w);
;                         *((u32x4*)(orow + half * 1024) + lane + 64 * j) = w; }
	s_waitcnt vmcnt(12)
	v_lshlrev_b32_e32 v88, 16, v44
	v_and_b32_e32 v89, 0xffff0000, v44
	v_lshlrev_b32_e32 v84, 16, v45
	v_and_b32_e32 v85, 0xffff0000, v45
	v_pk_mul_f32 v[44:45], v[88:89], v[88:89]
	v_pk_mul_f32 v[86:87], v[84:85], v[84:85]
	v_add_f32_e32 v44, v44, v45
	v_lshlrev_b32_e32 v82, 16, v46
	v_and_b32_e32 v83, 0xffff0000, v46
	v_add_f32_e32 v44, v44, v86
	v_lshlrev_b32_e32 v78, 16, v47
	v_and_b32_e32 v79, 0xffff0000, v47
	v_pk_mul_f32 v[46:47], v[82:83], v[82:83]
	v_add_f32_e32 v44, v44, v87
	v_add_f32_e32 v44, v44, v46
	v_pk_mul_f32 v[80:81], v[78:79], v[78:79]
	v_add_f32_e32 v44, v44, v47
	v_lshlrev_b32_e32 v96, 16, v40
	v_and_b32_e32 v97, 0xffff0000, v40
	v_add_f32_e32 v44, v44, v80
	v_lshlrev_b32_e32 v92, 16, v41
	v_and_b32_e32 v93, 0xffff0000, v41
	v_pk_mul_f32 v[40:41], v[96:97], v[96:97]
	v_add_f32_e32 v44, v44, v81
	v_add_f32_e32 v40, v44, v40
	v_pk_mul_f32 v[94:95], v[92:93], v[92:93]
	v_add_f32_e32 v40, v40, v41
	v_lshlrev_b32_e32 v90, 16, v42
	v_and_b32_e32 v91, 0xffff0000, v42
	v_add_f32_e32 v40, v40, v94
	v_lshlrev_b32_e32 v74, 16, v43
	v_and_b32_e32 v75, 0xffff0000, v43
	v_pk_mul_f32 v[42:43], v[90:91], v[90:91]
	v_add_f32_e32 v40, v40, v95
	v_add_f32_e32 v40, v40, v42
	v_pk_mul_f32 v[76:77], v[74:75], v[74:75]
	v_add_f32_e32 v40, v40, v43
	v_add_f32_e32 v40, v40, v76
	v_add_f32_e32 v40, v40, v77
	ds_bpermute_b32 v41, v62, v40
	s_ashr_i32 s11, s10, 31
	v_lshlrev_b32_e32 v86, 16, v32
	v_and_b32_e32 v87, 0xffff0000, v32
	v_pk_mul_f32 v[100:101], v[86:87], v[86:87]
	s_waitcnt lgkmcnt(0)
	v_add_f32_e32 v40, v40, v41
	ds_bpermute_b32 v41, v63, v40
	s_waitcnt lgkmcnt(0)
	v_add_f32_e32 v40, v40, v41
	ds_bpermute_b32 v41, v64, v40
	s_waitcnt lgkmcnt(0)
	v_add_f32_e32 v40, v40, v41
	ds_bpermute_b32 v41, v65, v40
	s_waitcnt lgkmcnt(0)
	v_add_f32_e32 v40, v40, v41
	ds_bpermute_b32 v41, v66, v40
	s_waitcnt lgkmcnt(0)
	v_add_f32_e32 v40, v40, v41
	ds_bpermute_b32 v41, v67, v40
	s_waitcnt lgkmcnt(0)
	v_add_f32_e32 v40, v40, v41
	v_fmamk_f32 v40, v40, 0x3a800000, v68
	v_mul_f32_e32 v41, 0x4f800000, v40
	v_cmp_gt_f32_e32 vcc, s15, v40
	s_nop 1
	v_cndmask_b32_e32 v40, v40, v41, vcc
	v_sqrt_f32_e32 v41, v40
	s_nop 0
	v_add_u32_e32 v42, -1, v41
	v_fma_f32 v44, -v42, v41, v40
	v_add_u32_e32 v43, 1, v41
	v_cmp_ge_f32_e64 s[0:1], 0, v44
	s_nop 1
	v_cndmask_b32_e64 v42, v41, v42, s[0:1]
	v_fma_f32 v41, -v43, v41, v40
	v_cmp_lt_f32_e64 s[0:1], 0, v41
	s_nop 1
	v_cndmask_b32_e64 v41, v42, v43, s[0:1]
	v_mul_f32_e32 v42, 0x37800000, v41
	v_cndmask_b32_e32 v41, v41, v42, vcc
	v_cmp_class_f32_e32 vcc, v40, v69
	s_nop 1
	v_cndmask_b32_e32 v40, v41, v40, vcc
	v_div_scale_f32 v41, s[0:1], v40, v40, 1.0
	v_rcp_f32_e32 v42, v41
	s_lshl_b64 s[0:1], s[10:11], 12
	v_lshl_add_u64 v[76:77], v[48:49], 0, s[0:1]
	v_fma_f32 v43, -v41, v42, 1.0
	v_fmac_f32_e32 v42, v43, v42
	v_div_scale_f32 v43, vcc, 1.0, v40, 1.0
	v_mul_f32_e32 v44, v43, v42
	v_fma_f32 v45, -v41, v44, v43
	v_fmac_f32_e32 v44, v45, v42
	v_fma_f32 v41, -v41, v44, v43
	v_div_fmas_f32 v41, v41, v42, v44
	v_div_fixup_f32 v80, v41, v40, 1.0
	v_pk_mul_f32 v[40:41], v[80:81], v[88:89] op_sel_hi:[0,1]
	v_pk_mul_f32 v[42:43], v[80:81], v[84:85] op_sel_hi:[0,1]
	v_pk_mul_f32 v[40:41], v[40:41], v[120:121]
	v_pk_mul_f32 v[42:43], v[42:43], v[122:123]
	v_cvt_pk_bf16_f32 v40, v40, v41
	v_cvt_pk_bf16_f32 v41, v42, v43
	v_pk_mul_f32 v[42:43], v[80:81], v[82:83] op_sel_hi:[0,1]
	v_pk_mul_f32 v[44:45], v[80:81], v[78:79] op_sel_hi:[0,1]
	v_pk_mul_f32 v[42:43], v[42:43], v[124:125]
	v_pk_mul_f32 v[44:45], v[44:45], v[126:127]
	v_cvt_pk_bf16_f32 v42, v42, v43
	v_cvt_pk_bf16_f32 v43, v44, v45
	global_store_dwordx4 v[76:77], v[40:43], off
	s_nop 1
	s_nop 0
	v_lshlrev_b32_e32 v78, 16, v36
	v_and_b32_e32 v79, 0xffff0000, v36
	v_lshlrev_b32_e32 v60, 16, v39
	v_and_b32_e32 v61, 0xffff0000, v39
	v_lshlrev_b32_e32 v70, 16, v38
	v_and_b32_e32 v71, 0xffff0000, v38
	v_lshlrev_b32_e32 v72, 16, v37
	v_and_b32_e32 v73, 0xffff0000, v37
	v_pk_mul_f32 v[38:39], v[78:79], v[78:79]
	v_pk_mul_f32 v[36:37], v[72:73], v[72:73]
	v_add_f32_e32 v38, v38, v39
	v_add_f32_e32 v36, v38, v36
	v_lshlrev_b32_e32 v58, 16, v35
	v_and_b32_e32 v59, 0xffff0000, v35
	v_lshlrev_b32_e32 v82, 16, v34
	v_and_b32_e32 v83, 0xffff0000, v34
	v_pk_mul_f32 v[34:35], v[70:71], v[70:71]
	v_add_f32_e32 v36, v36, v37
	v_add_f32_e32 v34, v36, v34
	v_lshlrev_b32_e32 v84, 16, v33
	v_and_b32_e32 v85, 0xffff0000, v33
	v_pk_mul_f32 v[32:33], v[60:61], v[60:61]
	v_add_f32_e32 v34, v34, v35
	v_add_f32_e32 v32, v34, v32
	v_add_f32_e32 v32, v32, v33
	v_add_f32_e32 v32, v32, v100
	v_pk_mul_f32 v[98:99], v[84:85], v[84:85]
	v_add_f32_e32 v32, v32, v101
	v_add_f32_e32 v32, v32, v98
	v_add_f32_e32 v81, v32, v99
	v_pk_mul_f32 v[32:33], v[80:81], v[96:97] op_sel_hi:[0,1]
	v_pk_mul_f32 v[34:35], v[80:81], v[92:93] op_sel_hi:[0,1]
	v_pk_mul_f32 v[36:37], v[80:81], v[90:91] op_sel_hi:[0,1]
	v_pk_mul_f32 v[38:39], v[80:81], v[74:75] op_sel_hi:[0,1]
	v_pk_mul_f32 v[94:95], v[82:83], v[82:83]
	v_pk_mul_f32 v[88:89], v[58:59], v[58:59]
	v_pk_mul_f32 v[32:33], v[32:33], v[128:129]
	v_pk_mul_f32 v[34:35], v[34:35], v[130:131]
	v_pk_mul_f32 v[36:37], v[36:37], v[132:133]
	v_pk_mul_f32 v[38:39], v[38:39], v[134:135]
	v_cvt_pk_bf16_f32 v32, v32, v33
	v_cvt_pk_bf16_f32 v33, v34, v35
	v_cvt_pk_bf16_f32 v34, v36, v37
	v_cvt_pk_bf16_f32 v35, v38, v39
	global_store_dwordx4 v[76:77], v[32:35], off offset:1024
	s_nop 1
	s_nop 0
	v_add_f32_e32 v40, v81, v94
	v_add_f32_e32 v40, v40, v95
	v_add_f32_e32 v40, v40, v88
	v_add_f32_e32 v40, v40, v89
	ds_bpermute_b32 v41, v62, v40
	s_waitcnt lgkmcnt(0)
; __global__ void __launch_bounds__(NTHR, 2) hymba_fwd(Params P) {
;     ...
;                     float v[16]; float s = 0.f;
; #pragma unroll
;                     for (int j = 0; j < 2; ++j) { const u32x4 qq = q[u][half][j];
;                         v[8 * j + 0] = bflo(qq.x); v[8 * j + 1] = bfhi(qq.x); v[8 * j + 2] = bflo(qq.y); v[8 * j + 3] = bfhi(qq.y); v[8 * j + 4] = bflo(qq.z); v[8 * j + 5] = bfhi(qq.z); v[8 * j + 6] = bflo(qq.w); v[8 * j + 7] = bfhi(qq.w); }
; #pragma unroll
;                     for (int j = 0; j < 16; ++j) s += v[j] * v[j];
;                     const float rs = 1.f / sqrtf(wave_sum(s) * (1.f / 1024.f) + EPS);
; #pragma unroll
;                     for (int j = 0; j < 2; ++j) { const f32x4 ga = *(const f32x4*)(gg + 8 * lane + 512 * j), gb = *(const f32x4*)(gg + 8 * lane + 512 * j + 4); u32x4 w;
;                         w.x = pk2(v[8 * j + 0] * rs * ga.x, v[8 * j + 1] * rs * ga.y); w.y = pk2(v[8 * j + 2] * rs * ga.z, v[8 * j + 3] * rs * ga.w);
;                         w.z = pk2(v[8 * j + 4] * rs * gb.x, v[8 * j + 5] * rs * gb.y); w.w = pk2(v[8 * j + 6] * rs * gb.z, v[8 * j + 7] * rs * gb.w);
;                         *((u32x4*)(orow + half * 1024) + lane + 64 * j) = w; }
	v_add_f32_e32 v40, v40, v41
	ds_bpermute_b32 v41, v63, v40
	s_waitcnt lgkmcnt(0)
	v_add_f32_e32 v40, v40, v41
	ds_bpermute_b32 v41, v64, v40
	s_waitcnt lgkmcnt(0)
	v_add_f32_e32 v40, v40, v41
	ds_bpermute_b32 v41, v65, v40
	s_waitcnt lgkmcnt(0)
	v_add_f32_e32 v40, v40, v41
	ds_bpermute_b32 v41, v66, v40
	s_waitcnt lgkmcnt(0)
	v_add_f32_e32 v40, v40, v41
	ds_bpermute_b32 v41, v67, v40
	s_waitcnt lgkmcnt(0)
	v_add_f32_e32 v40, v40, v41
	v_fmamk_f32 v40, v40, 0x3a800000, v68
	v_mul_f32_e32 v41, 0x4f800000, v40
	v_cmp_gt_f32_e32 vcc, s15, v40
	s_nop 1
	v_cndmask_b32_e32 v40, v40, v41, vcc
	v_sqrt_f32_e32 v41, v40
	s_nop 0
	v_add_u32_e32 v42, -1, v41
	v_add_u32_e32 v43, 1, v41
	v_fma_f32 v44, -v42, v41, v40
	v_fma_f32 v45, -v43, v41, v40
	v_cmp_ge_f32_e64 s[0:1], 0, v44
	s_nop 1
	v_cndmask_b32_e64 v41, v41, v42, s[0:1]
	v_cmp_lt_f32_e64 s[0:1], 0, v45
	s_nop 1
	v_cndmask_b32_e64 v41, v41, v43, s[0:1]
	v_mul_f32_e32 v42, 0x37800000, v41
	v_cndmask_b32_e32 v41, v41, v42, vcc
	v_cmp_class_f32_e32 vcc, v40, v69
	s_nop 1
	v_cndmask_b32_e32 v40, v41, v40, vcc
	v_div_scale_f32 v41, s[0:1], v40, v40, 1.0
	v_rcp_f32_e32 v42, v41
	v_div_scale_f32 v43, vcc, 1.0, v40, 1.0
	v_fma_f32 v44, -v41, v42, 1.0
	v_fmac_f32_e32 v42, v44, v42
	v_mul_f32_e32 v44, v43, v42
	v_fma_f32 v45, -v41, v44, v43
	v_fmac_f32_e32 v44, v45, v42
	v_fma_f32 v41, -v41, v44, v43
	v_div_fmas_f32 v41, v41, v42, v44
	v_div_fixup_f32 v40, v41, v40, 1.0
	v_pk_mul_f32 v[42:43], v[40:41], v[78:79] op_sel_hi:[0,1]
	v_pk_mul_f32 v[44:45], v[40:41], v[72:73] op_sel_hi:[0,1]
	v_pk_mul_f32 v[46:47], v[40:41], v[70:71] op_sel_hi:[0,1]
	v_pk_mul_f32 v[60:61], v[40:41], v[60:61] op_sel_hi:[0,1]
	v_pk_mul_f32 v[36:37], v[42:43], v[136:137]
	v_pk_mul_f32 v[38:39], v[44:45], v[138:139]
	v_pk_mul_f32 v[42:43], v[46:47], v[140:141]
	v_pk_mul_f32 v[44:45], v[60:61], v[142:143]
	v_cvt_pk_bf16_f32 v32, v36, v37
	v_cvt_pk_bf16_f32 v33, v38, v39
	v_cvt_pk_bf16_f32 v34, v42, v43
	v_cvt_pk_bf16_f32 v35, v44, v45
	global_store_dwordx4 v[76:77], v[32:35], off offset:2048
	s_nop 1
	s_nop 0
	v_pk_mul_f32 v[42:43], v[40:41], v[86:87] op_sel_hi:[0,1]
	v_pk_mul_f32 v[44:45], v[40:41], v[84:85] op_sel_hi:[0,1]
	v_pk_mul_f32 v[46:47], v[40:41], v[82:83] op_sel_hi:[0,1]
	v_pk_mul_f32 v[40:41], v[40:41], v[58:59] op_sel_hi:[0,1]
	v_pk_mul_f32 v[32:33], v[42:43], v[144:145]
	v_pk_mul_f32 v[34:35], v[44:45], v[146:147]
	v_pk_mul_f32 v[36:37], v[46:47], v[148:149]
	v_pk_mul_f32 v[38:39], v[40:41], v[150:151]
	v_cvt_pk_bf16_f32 v32, v32, v33
	v_cvt_pk_bf16_f32 v33, v34, v35
	v_cvt_pk_bf16_f32 v34, v36, v37
	v_cvt_pk_bf16_f32 v35, v38, v39
	global_store_dwordx4 v[76:77], v[32:35], off offset:3072
	s_nop 1
	s_cmp_gt_i32 s8, 0x807f
	s_cbranch_scc0 .LBB0_626

; __global__ void __launch_bounds__(NTHR, 2) hymba_fwd(Params P) {
;     ...
;             for (int u = 0; u < 4; ++u) { const int t = tt[u]; if (t >= TT) continue;
;                 bf16_t* orow = MIXIN + (size_t)t * MIXW;
; #pragma unroll
;                 for (int half = 0; half < 2; ++half) {
;                     const float* gg = half ? P.sb_norm_g : P.ssd_norm_g;
;                     float v[16]; float s = 0.f;
; #pragma unroll
;                     for (int j = 0; j < 2; ++j) { const u32x4 qq = q[u][half][j];
;                         v[8 * j + 0] = bflo(qq.x); v[8 * j + 1] = bfhi(qq.x); v[8 * j + 2] = bflo(qq.y); v[8 * j + 3] = bfhi(qq.y); v[8 * j + 4] = bflo(qq.z); v[8 * j + 5] = bfhi(qq.z); v[8 * j + 6] = bflo(qq.w); v[8 * j + 7] = bfhi(qq.w); }
; #pragma unroll
;                     for (int j = 0; j < 16; ++j) s += v[j] * v[j];
;                     const float rs = 1.f / sqrtf(wave_sum(s) * (1.f / 1024.f) + EPS);
; #pragma unroll
;                     for (int j = 0; j < 2; ++j) { const f32x4 ga = *(const f32x4*)(gg + 8 * lane + 512 * j), gb = *(const f32x4*)(gg + 8 * lane + 512 * j + 4); u32x4 w;
;                         w.x = pk2(v[8 * j + 0] * rs * ga.x, v[8 * j + 1] * rs * ga.y); w.y = pk2(v[8 * j + 2] * rs * ga.z, v[8 * j + 3] * rs * ga.w);
;                         w.z = pk2(v[8 * j + 4] * rs * gb.x, v[8 * j + 5] * rs * gb.y); w.w = pk2(v[8 * j + 6] * rs * gb.z, v[8 * j + 7] * rs * gb.w);
;                         *((u32x4*)(orow + half * 1024) + lane + 64 * j) = w; }
.LBB0_626:
	s_waitcnt vmcnt(8)
	v_lshlrev_b32_e32 v72, 16, v28
	v_and_b32_e32 v73, 0xffff0000, v28
	v_lshlrev_b32_e32 v60, 16, v29
	v_and_b32_e32 v61, 0xffff0000, v29
	v_pk_mul_f32 v[28:29], v[72:73], v[72:73]
	v_pk_mul_f32 v[70:71], v[60:61], v[60:61]
	v_add_f32_e32 v28, v28, v29
	v_lshlrev_b32_e32 v58, 16, v30
	v_and_b32_e32 v59, 0xffff0000, v30
	v_add_f32_e32 v28, v28, v70
	v_lshlrev_b32_e32 v44, 16, v31
	v_and_b32_e32 v45, 0xffff0000, v31
	v_pk_mul_f32 v[30:31], v[58:59], v[58:59]
	v_add_f32_e32 v28, v28, v71
	v_add_f32_e32 v28, v28, v30
	v_pk_mul_f32 v[46:47], v[44:45], v[44:45]
	v_add_f32_e32 v28, v28, v31
	v_lshlrev_b32_e32 v80, 16, v24
	v_and_b32_e32 v81, 0xffff0000, v24
	v_add_f32_e32 v28, v28, v46
	v_lshlrev_b32_e32 v76, 16, v25
	v_and_b32_e32 v77, 0xffff0000, v25
	v_pk_mul_f32 v[24:25], v[80:81], v[80:81]
	v_add_f32_e32 v28, v28, v47
	v_add_f32_e32 v24, v28, v24
	v_pk_mul_f32 v[78:79], v[76:77], v[76:77]
	v_add_f32_e32 v24, v24, v25
	v_lshlrev_b32_e32 v74, 16, v26
	v_and_b32_e32 v75, 0xffff0000, v26
	v_add_f32_e32 v24, v24, v78
	v_lshlrev_b32_e32 v40, 16, v27
	v_and_b32_e32 v41, 0xffff0000, v27
	v_pk_mul_f32 v[26:27], v[74:75], v[74:75]
	v_add_f32_e32 v24, v24, v79
	v_add_f32_e32 v24, v24, v26
	v_pk_mul_f32 v[42:43], v[40:41], v[40:41]
	v_add_f32_e32 v24, v24, v27
	v_add_f32_e32 v24, v24, v42
	v_add_f32_e32 v24, v24, v43
	ds_bpermute_b32 v25, v62, v24
	s_ashr_i32 s9, s8, 31
	v_lshlrev_b32_e32 v70, 16, v16
	v_and_b32_e32 v71, 0xffff0000, v16
	v_pk_mul_f32 v[84:85], v[70:71], v[70:71]
	s_waitcnt lgkmcnt(0)
	v_add_f32_e32 v24, v24, v25
	ds_bpermute_b32 v25, v63, v24
	s_waitcnt lgkmcnt(0)
	v_add_f32_e32 v24, v24, v25
	ds_bpermute_b32 v25, v64, v24
	s_waitcnt lgkmcnt(0)
	v_add_f32_e32 v24, v24, v25
	ds_bpermute_b32 v25, v65, v24
	s_waitcnt lgkmcnt(0)
	v_add_f32_e32 v24, v24, v25
	ds_bpermute_b32 v25, v66, v24
	s_waitcnt lgkmcnt(0)
	v_add_f32_e32 v24, v24, v25
	ds_bpermute_b32 v25, v67, v24
	s_waitcnt lgkmcnt(0)
	v_add_f32_e32 v24, v24, v25
	v_fmamk_f32 v24, v24, 0x3a800000, v68
	v_mul_f32_e32 v25, 0x4f800000, v24
	v_cmp_gt_f32_e32 vcc, s15, v24
	s_nop 1
	v_cndmask_b32_e32 v24, v24, v25, vcc
	v_sqrt_f32_e32 v25, v24
	s_nop 0
	v_add_u32_e32 v26, -1, v25
	v_fma_f32 v28, -v26, v25, v24
	v_add_u32_e32 v27, 1, v25
	v_cmp_ge_f32_e64 s[0:1], 0, v28
	s_nop 1
	v_cndmask_b32_e64 v26, v25, v26, s[0:1]
	v_fma_f32 v25, -v27, v25, v24
	v_cmp_lt_f32_e64 s[0:1], 0, v25
	s_nop 1
	v_cndmask_b32_e64 v25, v26, v27, s[0:1]
	v_mul_f32_e32 v26, 0x37800000, v25
	v_cndmask_b32_e32 v25, v25, v26, vcc
	v_cmp_class_f32_e32 vcc, v24, v69
	s_nop 1
	v_cndmask_b32_e32 v24, v25, v24, vcc
	v_div_scale_f32 v25, s[0:1], v24, v24, 1.0
	v_rcp_f32_e32 v26, v25
	s_lshl_b64 s[0:1], s[8:9], 12
	v_lshl_add_u64 v[42:43], v[48:49], 0, s[0:1]
	v_fma_f32 v27, -v25, v26, 1.0
	v_fmac_f32_e32 v26, v27, v26
	v_div_scale_f32 v27, vcc, 1.0, v24, 1.0
	v_mul_f32_e32 v28, v27, v26
	v_fma_f32 v29, -v25, v28, v27
	v_fmac_f32_e32 v28, v29, v26
	v_fma_f32 v25, -v25, v28, v27
	v_div_fmas_f32 v25, v25, v26, v28
	v_div_fixup_f32 v46, v25, v24, 1.0
	v_pk_mul_f32 v[24:25], v[46:47], v[72:73] op_sel_hi:[0,1]
	v_pk_mul_f32 v[26:27], v[46:47], v[60:61] op_sel_hi:[0,1]
	v_pk_mul_f32 v[24:25], v[24:25], v[120:121]
	v_pk_mul_f32 v[26:27], v[26:27], v[122:123]
	v_cvt_pk_bf16_f32 v24, v24, v25
	v_cvt_pk_bf16_f32 v25, v26, v27
	v_pk_mul_f32 v[26:27], v[46:47], v[58:59] op_sel_hi:[0,1]
	v_pk_mul_f32 v[28:29], v[46:47], v[44:45] op_sel_hi:[0,1]
	v_pk_mul_f32 v[26:27], v[26:27], v[124:125]
	v_pk_mul_f32 v[28:29], v[28:29], v[126:127]
	v_cvt_pk_bf16_f32 v26, v26, v27
	v_cvt_pk_bf16_f32 v27, v28, v29
	global_store_dwordx4 v[42:43], v[24:27], off
	s_nop 1
	s_nop 0
	v_lshlrev_b32_e32 v44, 16, v20
	v_and_b32_e32 v45, 0xffff0000, v20
	v_lshlrev_b32_e32 v34, 16, v23
	v_and_b32_e32 v35, 0xffff0000, v23
	v_lshlrev_b32_e32 v36, 16, v22
	v_and_b32_e32 v37, 0xffff0000, v22
	v_lshlrev_b32_e32 v38, 16, v21
	v_and_b32_e32 v39, 0xffff0000, v21
	v_pk_mul_f32 v[22:23], v[44:45], v[44:45]
	v_pk_mul_f32 v[20:21], v[38:39], v[38:39]
	v_add_f32_e32 v22, v22, v23
	v_add_f32_e32 v20, v22, v20
	v_lshlrev_b32_e32 v32, 16, v19
	v_and_b32_e32 v33, 0xffff0000, v19
	v_lshlrev_b32_e32 v58, 16, v18
	v_and_b32_e32 v59, 0xffff0000, v18
	v_pk_mul_f32 v[18:19], v[36:37], v[36:37]
	v_add_f32_e32 v20, v20, v21
	v_add_f32_e32 v18, v20, v18
	v_lshlrev_b32_e32 v60, 16, v17
	v_and_b32_e32 v61, 0xffff0000, v17
	v_pk_mul_f32 v[16:17], v[34:35], v[34:35]
	v_add_f32_e32 v18, v18, v19
	v_add_f32_e32 v16, v18, v16
	v_add_f32_e32 v16, v16, v17
	v_add_f32_e32 v16, v16, v84
	v_pk_mul_f32 v[82:83], v[60:61], v[60:61]
	v_add_f32_e32 v16, v16, v85
	v_add_f32_e32 v16, v16, v82
	v_add_f32_e32 v47, v16, v83
	v_pk_mul_f32 v[16:17], v[46:47], v[80:81] op_sel_hi:[0,1]
	v_pk_mul_f32 v[18:19], v[46:47], v[76:77] op_sel_hi:[0,1]
	v_pk_mul_f32 v[20:21], v[46:47], v[74:75] op_sel_hi:[0,1]
	v_pk_mul_f32 v[22:23], v[46:47], v[40:41] op_sel_hi:[0,1]
	v_pk_mul_f32 v[78:79], v[58:59], v[58:59]
	v_pk_mul_f32 v[72:73], v[32:33], v[32:33]
	v_pk_mul_f32 v[16:17], v[16:17], v[128:129]
	v_pk_mul_f32 v[18:19], v[18:19], v[130:131]
	v_pk_mul_f32 v[20:21], v[20:21], v[132:133]
	v_pk_mul_f32 v[22:23], v[22:23], v[134:135]
	v_cvt_pk_bf16_f32 v16, v16, v17
	v_cvt_pk_bf16_f32 v17, v18, v19
	v_cvt_pk_bf16_f32 v18, v20, v21
	v_cvt_pk_bf16_f32 v19, v22, v23
	global_store_dwordx4 v[42:43], v[16:19], off offset:1024
	s_nop 1
	s_nop 0
	v_add_f32_e32 v24, v47, v78
	v_add_f32_e32 v24, v24, v79
	v_add_f32_e32 v24, v24, v72
	v_add_f32_e32 v24, v24, v73
	ds_bpermute_b32 v25, v62, v24
	s_waitcnt lgkmcnt(0)
	v_add_f32_e32 v24, v24, v25
	ds_bpermute_b32 v25, v63, v24
	s_waitcnt lgkmcnt(0)
; __global__ void __launch_bounds__(NTHR, 2) hymba_fwd(Params P) {
;     ...
;             for (int u = 0; u < 4; ++u) { const int t = tt[u]; if (t >= TT) continue;
;                 bf16_t* orow = MIXIN + (size_t)t * MIXW;
; #pragma unroll
;                 for (int half = 0; half < 2; ++half) {
;                     const float* gg = half ? P.sb_norm_g : P.ssd_norm_g;
;                     float v[16]; float s = 0.f;
; #pragma unroll
;                     for (int j = 0; j < 2; ++j) { const u32x4 qq = q[u][half][j];
;                         v[8 * j + 0] = bflo(qq.x); v[8 * j + 1] = bfhi(qq.x); v[8 * j + 2] = bflo(qq.y); v[8 * j + 3] = bfhi(qq.y); v[8 * j + 4] = bflo(qq.z); v[8 * j + 5] = bfhi(qq.z); v[8 * j + 6] = bflo(qq.w); v[8 * j + 7] = bfhi(qq.w); }
; #pragma unroll
;                     for (int j = 0; j < 16; ++j) s += v[j] * v[j];
;                     const float rs = 1.f / sqrtf(wave_sum(s) * (1.f / 1024.f) + EPS);
; #pragma unroll
;                     for (int j = 0; j < 2; ++j) { const f32x4 ga = *(const f32x4*)(gg + 8 * lane + 512 * j), gb = *(const f32x4*)(gg + 8 * lane + 512 * j + 4); u32x4 w;
;                         w.x = pk2(v[8 * j + 0] * rs * ga.x, v[8 * j + 1] * rs * ga.y); w.y = pk2(v[8 * j + 2] * rs * ga.z, v[8 * j + 3] * rs * ga.w);
;                         w.z = pk2(v[8 * j + 4] * rs * gb.x, v[8 * j + 5] * rs * gb.y); w.w = pk2(v[8 * j + 6] * rs * gb.z, v[8 * j + 7] * rs * gb.w);
;                         *((u32x4*)(orow + half * 1024) + lane + 64 * j) = w; }
;                 }
	v_add_f32_e32 v24, v24, v25
	ds_bpermute_b32 v25, v64, v24
	s_waitcnt lgkmcnt(0)
	v_add_f32_e32 v24, v24, v25
	ds_bpermute_b32 v25, v65, v24
	s_waitcnt lgkmcnt(0)
	v_add_f32_e32 v24, v24, v25
	ds_bpermute_b32 v25, v66, v24
	s_waitcnt lgkmcnt(0)
	v_add_f32_e32 v24, v24, v25
	ds_bpermute_b32 v25, v67, v24
	s_waitcnt lgkmcnt(0)
	v_add_f32_e32 v24, v24, v25
	v_fmamk_f32 v24, v24, 0x3a800000, v68
	v_mul_f32_e32 v25, 0x4f800000, v24
	v_cmp_gt_f32_e32 vcc, s15, v24
	s_nop 1
	v_cndmask_b32_e32 v24, v24, v25, vcc
	v_sqrt_f32_e32 v25, v24
	s_nop 0
	v_add_u32_e32 v26, -1, v25
	v_add_u32_e32 v27, 1, v25
	v_fma_f32 v28, -v26, v25, v24
	v_fma_f32 v29, -v27, v25, v24
	v_cmp_ge_f32_e64 s[0:1], 0, v28
	s_nop 1
	v_cndmask_b32_e64 v25, v25, v26, s[0:1]
	v_cmp_lt_f32_e64 s[0:1], 0, v29
	s_nop 1
	v_cndmask_b32_e64 v25, v25, v27, s[0:1]
	v_mul_f32_e32 v26, 0x37800000, v25
	v_cndmask_b32_e32 v25, v25, v26, vcc
	v_cmp_class_f32_e32 vcc, v24, v69
	s_nop 1
	v_cndmask_b32_e32 v24, v25, v24, vcc
	v_div_scale_f32 v25, s[0:1], v24, v24, 1.0
	v_rcp_f32_e32 v26, v25
	v_div_scale_f32 v27, vcc, 1.0, v24, 1.0
	v_fma_f32 v28, -v25, v26, 1.0
	v_fmac_f32_e32 v26, v28, v26
	v_mul_f32_e32 v28, v27, v26
	v_fma_f32 v29, -v25, v28, v27
	v_fmac_f32_e32 v28, v29, v26
	v_fma_f32 v25, -v25, v28, v27
	v_div_fmas_f32 v25, v25, v26, v28
	v_div_fixup_f32 v24, v25, v24, 1.0
	v_pk_mul_f32 v[26:27], v[24:25], v[44:45] op_sel_hi:[0,1]
	v_pk_mul_f32 v[28:29], v[24:25], v[38:39] op_sel_hi:[0,1]
	v_pk_mul_f32 v[30:31], v[24:25], v[36:37] op_sel_hi:[0,1]
	v_pk_mul_f32 v[34:35], v[24:25], v[34:35] op_sel_hi:[0,1]
	v_pk_mul_f32 v[20:21], v[26:27], v[136:137]
	v_pk_mul_f32 v[22:23], v[28:29], v[138:139]
	v_pk_mul_f32 v[26:27], v[30:31], v[140:141]
	v_pk_mul_f32 v[28:29], v[34:35], v[142:143]
	v_cvt_pk_bf16_f32 v16, v20, v21
	v_cvt_pk_bf16_f32 v17, v22, v23
	v_cvt_pk_bf16_f32 v18, v26, v27
	v_cvt_pk_bf16_f32 v19, v28, v29
	global_store_dwordx4 v[42:43], v[16:19], off offset:2048
	s_nop 1
	s_nop 0
	v_pk_mul_f32 v[26:27], v[24:25], v[70:71] op_sel_hi:[0,1]
	v_pk_mul_f32 v[28:29], v[24:25], v[60:61] op_sel_hi:[0,1]
	v_pk_mul_f32 v[30:31], v[24:25], v[58:59] op_sel_hi:[0,1]
	v_pk_mul_f32 v[24:25], v[24:25], v[32:33] op_sel_hi:[0,1]
	v_pk_mul_f32 v[16:17], v[26:27], v[144:145]
	v_pk_mul_f32 v[18:19], v[28:29], v[146:147]
	v_pk_mul_f32 v[20:21], v[30:31], v[148:149]
	v_pk_mul_f32 v[22:23], v[24:25], v[150:151]
	v_cvt_pk_bf16_f32 v16, v16, v17
	v_cvt_pk_bf16_f32 v17, v18, v19
	v_cvt_pk_bf16_f32 v18, v20, v21
	v_cvt_pk_bf16_f32 v19, v22, v23
	global_store_dwordx4 v[42:43], v[16:19], off offset:3072
	s_nop 1
	s_cmp_gt_i32 s6, 0x807f
	s_cbranch_scc1 .LBB0_621
.LBB0_627:
	s_waitcnt vmcnt(4)
	v_lshlrev_b32_e32 v38, 16, v12
	v_and_b32_e32 v39, 0xffff0000, v12
	v_lshlrev_b32_e32 v34, 16, v13
	v_and_b32_e32 v35, 0xffff0000, v13
	v_pk_mul_f32 v[12:13], v[38:39], v[38:39]
	v_pk_mul_f32 v[36:37], v[34:35], v[34:35]
	v_add_f32_e32 v12, v12, v13
	v_lshlrev_b32_e32 v32, 16, v14
	v_and_b32_e32 v33, 0xffff0000, v14
	v_add_f32_e32 v12, v12, v36
	v_lshlrev_b32_e32 v28, 16, v15
	v_and_b32_e32 v29, 0xffff0000, v15
	v_pk_mul_f32 v[14:15], v[32:33], v[32:33]
	v_add_f32_e32 v12, v12, v37
	v_add_f32_e32 v12, v12, v14
	v_pk_mul_f32 v[30:31], v[28:29], v[28:29]
	v_add_f32_e32 v12, v12, v15
	v_lshlrev_b32_e32 v46, 16, v8
	v_and_b32_e32 v47, 0xffff0000, v8
	v_add_f32_e32 v12, v12, v30
	v_lshlrev_b32_e32 v42, 16, v9
	v_and_b32_e32 v43, 0xffff0000, v9
	v_pk_mul_f32 v[8:9], v[46:47], v[46:47]
	v_add_f32_e32 v12, v12, v31
	v_add_f32_e32 v8, v12, v8
	v_pk_mul_f32 v[44:45], v[42:43], v[42:43]
	v_add_f32_e32 v8, v8, v9
	v_lshlrev_b32_e32 v40, 16, v10
	v_and_b32_e32 v41, 0xffff0000, v10
	v_add_f32_e32 v8, v8, v44
	v_lshlrev_b32_e32 v24, 16, v11
	v_and_b32_e32 v25, 0xffff0000, v11
	v_pk_mul_f32 v[10:11], v[40:41], v[40:41]
	v_add_f32_e32 v8, v8, v45
	v_add_f32_e32 v8, v8, v10
	v_pk_mul_f32 v[26:27], v[24:25], v[24:25]
	v_add_f32_e32 v8, v8, v11
	v_add_f32_e32 v8, v8, v26
	v_add_f32_e32 v8, v8, v27
	ds_bpermute_b32 v9, v62, v8
	s_ashr_i32 s7, s6, 31
	v_lshlrev_b32_e32 v36, 16, v0
	v_and_b32_e32 v37, 0xffff0000, v0
	v_pk_mul_f32 v[60:61], v[36:37], v[36:37]
	s_waitcnt lgkmcnt(0)
	v_add_f32_e32 v8, v8, v9
	ds_bpermute_b32 v9, v63, v8
	s_waitcnt lgkmcnt(0)
	v_add_f32_e32 v8, v8, v9
	ds_bpermute_b32 v9, v64, v8
	s_waitcnt lgkmcnt(0)
	v_add_f32_e32 v8, v8, v9
	ds_bpermute_b32 v9, v65, v8
	s_waitcnt lgkmcnt(0)
	v_add_f32_e32 v8, v8, v9
	ds_bpermute_b32 v9, v66, v8
	s_waitcnt lgkmcnt(0)
	v_add_f32_e32 v8, v8, v9
	ds_bpermute_b32 v9, v67, v8
	s_waitcnt lgkmcnt(0)
; __global__ void __launch_bounds__(NTHR, 2) hymba_fwd(Params P) {
;     ...
;             for (int u = 0; u < 4; ++u) { const int t = tt[u]; if (t >= TT) continue;
;                 bf16_t* orow = MIXIN + (size_t)t * MIXW;
; #pragma unroll
;                 for (int half = 0; half < 2; ++half) {
;                     const float* gg = half ? P.sb_norm_g : P.ssd_norm_g;
;                     float v[16]; float s = 0.f;
; #pragma unroll
;                     for (int j = 0; j < 2; ++j) { const u32x4 qq = q[u][half][j];
;                         v[8 * j + 0] = bflo(qq.x); v[8 * j + 1] = bfhi(qq.x); v[8 * j + 2] = bflo(qq.y); v[8 * j + 3] = bfhi(qq.y); v[8 * j + 4] = bflo(qq.z); v[8 * j + 5] = bfhi(qq.z); v[8 * j + 6] = bflo(qq.w); v[8 * j + 7] = bfhi(qq.w); }
; #pragma unroll
;                     for (int j = 0; j < 16; ++j) s += v[j] * v[j];
;                     const float rs = 1.f / sqrtf(wave_sum(s) * (1.f / 1024.f) + EPS);
; #pragma unroll
;                     for (int j = 0; j < 2; ++j) { const f32x4 ga = *(const f32x4*)(gg + 8 * lane + 512 * j), gb = *(const f32x4*)(gg + 8 * lane + 512 * j + 4); u32x4 w;
;                         w.x = pk2(v[8 * j + 0] * rs * ga.x, v[8 * j + 1] * rs * ga.y); w.y = pk2(v[8 * j + 2] * rs * ga.z, v[8 * j + 3] * rs * ga.w);
;                         w.z = pk2(v[8 * j + 4] * rs * gb.x, v[8 * j + 5] * rs * gb.y); w.w = pk2(v[8 * j + 6] * rs * gb.z, v[8 * j + 7] * rs * gb.w);
;                         *((u32x4*)(orow + half * 1024) + lane + 64 * j) = w; }
;                 }
	v_add_f32_e32 v8, v8, v9
	v_fmamk_f32 v8, v8, 0x3a800000, v68
	v_mul_f32_e32 v9, 0x4f800000, v8
	v_cmp_gt_f32_e32 vcc, s15, v8
	s_nop 1
	v_cndmask_b32_e32 v8, v8, v9, vcc
	v_sqrt_f32_e32 v9, v8
	s_nop 0
	v_add_u32_e32 v10, -1, v9
	v_fma_f32 v12, -v10, v9, v8
	v_add_u32_e32 v11, 1, v9
	v_cmp_ge_f32_e64 s[0:1], 0, v12
	s_nop 1
	v_cndmask_b32_e64 v10, v9, v10, s[0:1]
	v_fma_f32 v9, -v11, v9, v8
	v_cmp_lt_f32_e64 s[0:1], 0, v9
	s_nop 1
	v_cndmask_b32_e64 v9, v10, v11, s[0:1]
	v_mul_f32_e32 v10, 0x37800000, v9
	v_cndmask_b32_e32 v9, v9, v10, vcc
	v_cmp_class_f32_e32 vcc, v8, v69
	s_nop 1
	v_cndmask_b32_e32 v8, v9, v8, vcc
	v_div_scale_f32 v9, s[0:1], v8, v8, 1.0
	v_rcp_f32_e32 v10, v9
	s_lshl_b64 s[0:1], s[6:7], 12
	v_lshl_add_u64 v[26:27], v[48:49], 0, s[0:1]
	v_fma_f32 v11, -v9, v10, 1.0
	v_fmac_f32_e32 v10, v11, v10
	v_div_scale_f32 v11, vcc, 1.0, v8, 1.0
	v_mul_f32_e32 v12, v11, v10
	v_fma_f32 v13, -v9, v12, v11
	v_fmac_f32_e32 v12, v13, v10
	v_fma_f32 v9, -v9, v12, v11
	v_div_fmas_f32 v9, v9, v10, v12
	v_div_fixup_f32 v30, v9, v8, 1.0
	v_pk_mul_f32 v[8:9], v[30:31], v[38:39] op_sel_hi:[0,1]
	v_pk_mul_f32 v[10:11], v[30:31], v[34:35] op_sel_hi:[0,1]
	v_pk_mul_f32 v[8:9], v[8:9], v[120:121]
	v_pk_mul_f32 v[10:11], v[10:11], v[122:123]
	v_cvt_pk_bf16_f32 v8, v8, v9
	v_cvt_pk_bf16_f32 v9, v10, v11
	v_pk_mul_f32 v[10:11], v[30:31], v[32:33] op_sel_hi:[0,1]
	v_pk_mul_f32 v[12:13], v[30:31], v[28:29] op_sel_hi:[0,1]
	v_pk_mul_f32 v[10:11], v[10:11], v[124:125]
	v_pk_mul_f32 v[12:13], v[12:13], v[126:127]
	v_cvt_pk_bf16_f32 v10, v10, v11
	v_cvt_pk_bf16_f32 v11, v12, v13
	global_store_dwordx4 v[26:27], v[8:11], off
	s_nop 1
	s_nop 0
	v_lshlrev_b32_e32 v28, 16, v4
	v_and_b32_e32 v29, 0xffff0000, v4
	v_lshlrev_b32_e32 v18, 16, v7
	v_and_b32_e32 v19, 0xffff0000, v7
	v_lshlrev_b32_e32 v20, 16, v6
	v_and_b32_e32 v21, 0xffff0000, v6
	v_lshlrev_b32_e32 v22, 16, v5
	v_and_b32_e32 v23, 0xffff0000, v5
	v_pk_mul_f32 v[6:7], v[28:29], v[28:29]
	v_pk_mul_f32 v[4:5], v[22:23], v[22:23]
	v_add_f32_e32 v6, v6, v7
	v_add_f32_e32 v4, v6, v4
	v_lshlrev_b32_e32 v16, 16, v3
	v_and_b32_e32 v17, 0xffff0000, v3
	v_lshlrev_b32_e32 v32, 16, v2
	v_and_b32_e32 v33, 0xffff0000, v2
	v_pk_mul_f32 v[2:3], v[20:21], v[20:21]
	v_add_f32_e32 v4, v4, v5
	v_add_f32_e32 v2, v4, v2
	v_lshlrev_b32_e32 v34, 16, v1
	v_and_b32_e32 v35, 0xffff0000, v1
	v_pk_mul_f32 v[0:1], v[18:19], v[18:19]
	v_add_f32_e32 v2, v2, v3
	v_add_f32_e32 v0, v2, v0
	v_add_f32_e32 v0, v0, v1
	v_add_f32_e32 v0, v0, v60
	v_pk_mul_f32 v[58:59], v[34:35], v[34:35]
	v_add_f32_e32 v0, v0, v61
	v_add_f32_e32 v0, v0, v58
	v_add_f32_e32 v31, v0, v59
	v_pk_mul_f32 v[0:1], v[30:31], v[46:47] op_sel_hi:[0,1]
	v_pk_mul_f32 v[2:3], v[30:31], v[42:43] op_sel_hi:[0,1]
	v_pk_mul_f32 v[4:5], v[30:31], v[40:41] op_sel_hi:[0,1]
	v_pk_mul_f32 v[6:7], v[30:31], v[24:25] op_sel_hi:[0,1]
	v_pk_mul_f32 v[44:45], v[32:33], v[32:33]
	v_pk_mul_f32 v[38:39], v[16:17], v[16:17]
	v_pk_mul_f32 v[0:1], v[0:1], v[128:129]
	v_pk_mul_f32 v[2:3], v[2:3], v[130:131]
	v_pk_mul_f32 v[4:5], v[4:5], v[132:133]
	v_pk_mul_f32 v[6:7], v[6:7], v[134:135]
	v_cvt_pk_bf16_f32 v0, v0, v1
	v_cvt_pk_bf16_f32 v1, v2, v3
	v_cvt_pk_bf16_f32 v2, v4, v5
	v_cvt_pk_bf16_f32 v3, v6, v7
	global_store_dwordx4 v[26:27], v[0:3], off offset:1024
	s_nop 1
	s_nop 0
	v_add_f32_e32 v8, v31, v44
	v_add_f32_e32 v8, v8, v45
	v_add_f32_e32 v8, v8, v38
	v_add_f32_e32 v8, v8, v39
	ds_bpermute_b32 v9, v62, v8
	s_waitcnt lgkmcnt(0)
	v_add_f32_e32 v8, v8, v9
	ds_bpermute_b32 v9, v63, v8
	s_waitcnt lgkmcnt(0)
	v_add_f32_e32 v8, v8, v9
	ds_bpermute_b32 v9, v64, v8
	s_waitcnt lgkmcnt(0)
	v_add_f32_e32 v8, v8, v9
	ds_bpermute_b32 v9, v65, v8
	s_waitcnt lgkmcnt(0)
	v_add_f32_e32 v8, v8, v9
	ds_bpermute_b32 v9, v66, v8
	s_waitcnt lgkmcnt(0)
	v_add_f32_e32 v8, v8, v9
	ds_bpermute_b32 v9, v67, v8
	s_waitcnt lgkmcnt(0)
	v_add_f32_e32 v8, v8, v9
	v_fmamk_f32 v8, v8, 0x3a800000, v68
	v_mul_f32_e32 v9, 0x4f800000, v8
	v_cmp_gt_f32_e32 vcc, s15, v8
	s_nop 1
	v_cndmask_b32_e32 v8, v8, v9, vcc
	v_sqrt_f32_e32 v9, v8
	s_nop 0
	v_add_u32_e32 v10, -1, v9
	v_add_u32_e32 v11, 1, v9
	v_fma_f32 v12, -v10, v9, v8
	v_fma_f32 v13, -v11, v9, v8
	v_cmp_ge_f32_e64 s[0:1], 0, v12
	s_nop 1
	v_cndmask_b32_e64 v9, v9, v10, s[0:1]
	v_cmp_lt_f32_e64 s[0:1], 0, v13
	s_nop 1
	v_cndmask_b32_e64 v9, v9, v11, s[0:1]
	v_mul_f32_e32 v10, 0x37800000, v9
	v_cndmask_b32_e32 v9, v9, v10, vcc
	v_cmp_class_f32_e32 vcc, v8, v69
	s_nop 1
	v_cndmask_b32_e32 v8, v9, v8, vcc
	v_div_scale_f32 v9, s[0:1], v8, v8, 1.0
	v_rcp_f32_e32 v10, v9
	v_div_scale_f32 v11, vcc, 1.0, v8, 1.0
	v_fma_f32 v12, -v9, v10, 1.0
	v_fmac_f32_e32 v10, v12, v10
	v_mul_f32_e32 v12, v11, v10
	v_fma_f32 v13, -v9, v12, v11
	v_fmac_f32_e32 v12, v13, v10
	v_fma_f32 v9, -v9, v12, v11
	v_div_fmas_f32 v9, v9, v10, v12
	v_div_fixup_f32 v8, v9, v8, 1.0
	v_pk_mul_f32 v[10:11], v[8:9], v[28:29] op_sel_hi:[0,1]
	v_pk_mul_f32 v[12:13], v[8:9], v[22:23] op_sel_hi:[0,1]
	v_pk_mul_f32 v[14:15], v[8:9], v[20:21] op_sel_hi:[0,1]
	v_pk_mul_f32 v[18:19], v[8:9], v[18:19] op_sel_hi:[0,1]
	v_pk_mul_f32 v[4:5], v[10:11], v[136:137]
	v_pk_mul_f32 v[6:7], v[12:13], v[138:139]
	v_pk_mul_f32 v[10:11], v[14:15], v[140:141]
	v_pk_mul_f32 v[12:13], v[18:19], v[142:143]
	v_cvt_pk_bf16_f32 v0, v4, v5
	v_cvt_pk_bf16_f32 v1, v6, v7
	v_cvt_pk_bf16_f32 v2, v10, v11
	v_cvt_pk_bf16_f32 v3, v12, v13
	global_store_dwordx4 v[26:27], v[0:3], off offset:2048
	s_nop 1
	s_nop 0
	v_pk_mul_f32 v[10:11], v[8:9], v[36:37] op_sel_hi:[0,1]
	v_pk_mul_f32 v[12:13], v[8:9], v[34:35] op_sel_hi:[0,1]
	v_pk_mul_f32 v[14:15], v[8:9], v[32:33] op_sel_hi:[0,1]
	v_pk_mul_f32 v[8:9], v[8:9], v[16:17] op_sel_hi:[0,1]
	v_pk_mul_f32 v[0:1], v[10:11], v[144:145]
	v_pk_mul_f32 v[2:3], v[12:13], v[146:147]
	v_pk_mul_f32 v[4:5], v[14:15], v[148:149]
	v_pk_mul_f32 v[6:7], v[8:9], v[150:151]
	v_cvt_pk_bf16_f32 v0, v0, v1
	v_cvt_pk_bf16_f32 v1, v2, v3
	v_cvt_pk_bf16_f32 v2, v4, v5
	v_cvt_pk_bf16_f32 v3, v6, v7
	global_store_dwordx4 v[26:27], v[0:3], off offset:3072
	s_nop 1
	s_branch .LBB0_621

; __global__ void __launch_bounds__(NTHR, 2) hymba_fwd(Params P) {
;     ...
;         for (int t0 = gw; t0 < TT; t0 += 2 * NGW) {
;             f32x4 m[2][4], xv[2][4]; int tt[2];
; #pragma unroll
;             for (int u = 0; u < 2; ++u) { const int t = t0 + u * NGW; tt[u] = t; const int tc = t < TT ? t : TT - 1;
;                 const int b = tc / LL, p = tc - b * LL;
;                 const float* src = (p < NMETA) ? P.meta + (size_t)p * 1024 : P.x + ((size_t)b * SEQ + p - NMETA) * 1024;
; #pragma unroll
;                 for (int j = 0; j < 4; ++j) { const u32x2 mq = __builtin_nontemporal_load((const u32x2*)(MIX + (size_t)tc * 1024) + lane + 64 * j);
;                     m[u][j] = (f32x4){bflo(mq.x), bfhi(mq.x), bflo(mq.y), bfhi(mq.y)}; xv[u][j] = __builtin_nontemporal_load((const f32x4*)src + lane + 64 * j); } }
; #pragma unroll
;             for (int u = 0; u < 2; ++u) { const int t = tt[u]; if (t >= TT) continue;
;                 float s = 0.f; f32x4 hv[4];
; #pragma unroll
;                 for (int j = 0; j < 4; ++j) s += (m[u][j].x * m[u][j].x + m[u][j].y * m[u][j].y) + (m[u][j].z * m[u][j].z + m[u][j].w * m[u][j].w);
;                 const float rs = 1.f / sqrtf(wave_sum(s) * (1.f / 1024.f) + EPS);
; #pragma unroll
;                 for (int j = 0; j < 4; ++j) { const f32x4 gg = *((const f32x4*)P.mix_post_g + lane + 64 * j);
;                     hv[j] = xv[u][j] + m[u][j] * rs * gg; u32x2 hq; hq.x = pk2(hv[j].x, hv[j].y); hq.y = pk2(hv[j].z, hv[j].w); __builtin_nontemporal_store(hq, (u32x2*)(H1 + (size_t)t * 1024) + lane + 64 * j); }
;                 rms_store_bf16(hv, P.ffn_pre_g, XN + (size_t)t * 1024, lane);
.LBB0_795:
	s_or_b64 exec, exec, s[6:7]
	v_readlane_b32 s8, v237, 8
	v_readlane_b32 s9, v237, 9
	s_add_u32 s92, s8, 0x17f00000
	s_addc_u32 s93, s9, 0
	s_and_b64 vcc, exec, s[4:5]
	v_readlane_b32 s10, v237, 10
	v_readlane_b32 s11, v237, 11
	s_waitcnt lgkmcnt(0)
	s_barrier
	s_cbranch_vccnz .LBB0_808
	v_ashrrev_i32_e32 v153, 31, v152
	v_lshlrev_b64 v[0:1], 3, v[152:153]
	v_lshl_add_u64 v[32:33], s[2:3], 0, v[0:1]
	v_readlane_b32 s2, v237, 54
	v_readlane_b32 s3, v237, 55
	v_readlane_b32 s4, v237, 30
	v_lshl_add_u64 v[36:37], s[92:93], 0, v[0:1]
	v_lshl_add_u64 v[38:39], s[2:3], 0, v[0:1]
	v_mbcnt_hi_u32_b32 v0, -1, v180
	v_lshlrev_b64 v[2:3], 4, v[152:153]
	v_readlane_b32 s12, v237, 38
	v_readlane_b32 s13, v237, 39
	v_readlane_b32 s14, v237, 40
	v_readlane_b32 s15, v237, 41
	v_and_b32_e32 v1, 64, v0
	v_lshl_add_u64 v[34:35], s[12:13], 0, v[2:3]
	v_lshl_add_u64 v[40:41], s[14:15], 0, v[2:3]
	v_add_u32_e32 v1, 64, v1
	v_xor_b32_e32 v2, 1, v0
	v_cmp_lt_i32_e32 vcc, v2, v1
	v_readlane_b32 s5, v237, 31
	v_readlane_b32 s6, v237, 32
	v_cndmask_b32_e32 v2, v0, v2, vcc
	v_lshlrev_b32_e32 v50, 2, v2
	v_xor_b32_e32 v2, 2, v0
	v_cmp_lt_i32_e32 vcc, v2, v1
	v_readlane_b32 s7, v237, 33
	v_readlane_b32 s4, v237, 8
	v_cndmask_b32_e32 v2, v0, v2, vcc
	v_lshlrev_b32_e32 v51, 2, v2
	v_xor_b32_e32 v2, 4, v0
	v_cmp_lt_i32_e32 vcc, v2, v1
	v_readlane_b32 s6, v237, 10
	s_mov_b32 s3, 0
	v_cndmask_b32_e32 v2, v0, v2, vcc
	v_lshlrev_b32_e32 v52, 2, v2
	v_xor_b32_e32 v2, 8, v0
	v_cmp_lt_i32_e32 vcc, v2, v1
	s_lshl_b32 s20, s6, 4
	v_mov_b32_e32 v56, 0x358637bd
	v_cndmask_b32_e32 v2, v0, v2, vcc
	v_lshlrev_b32_e32 v53, 2, v2
	v_xor_b32_e32 v2, 16, v0
	v_cmp_lt_i32_e32 vcc, v2, v1
	s_mov_b32 s21, 0xf800000
	v_mov_b32_e32 v57, 0x260
	v_cndmask_b32_e32 v2, v0, v2, vcc
	v_lshlrev_b32_e32 v54, 2, v2
	v_xor_b32_e32 v2, 32, v0
	v_cmp_lt_i32_e32 vcc, v2, v1
	s_mov_b32 s6, s70
	v_readlane_b32 s8, v237, 34
	v_cndmask_b32_e32 v0, v0, v2, vcc
	v_lshlrev_b32_e32 v55, 2, v0
	v_readlane_b32 s9, v237, 35
	v_readlane_b32 s10, v237, 36
	v_readlane_b32 s11, v237, 37
	v_readlane_b32 s16, v237, 42
	v_readlane_b32 s17, v237, 43
	v_readlane_b32 s18, v237, 44
	v_readlane_b32 s19, v237, 45
	v_readlane_b32 s5, v237, 9
	v_readlane_b32 s7, v237, 11
	global_load_dwordx4 v[96:99], v[34:35], off
	global_load_dwordx4 v[100:103], v[34:35], off offset:1024
	global_load_dwordx4 v[104:107], v[34:35], off offset:2048
	global_load_dwordx4 v[108:111], v[34:35], off offset:3072
	global_load_dwordx4 v[112:115], v[40:41], off
	global_load_dwordx4 v[116:119], v[40:41], off offset:1024
	global_load_dwordx4 v[120:123], v[40:41], off offset:2048
	global_load_dwordx4 v[124:127], v[40:41], off offset:3072
	s_waitcnt vmcnt(0)
	s_branch .LBB0_798

; __global__ void __launch_bounds__(NTHR, 2) hymba_fwd(Params P) {
;     ...
;             for (int u = 0; u < 2; ++u) { const int t = t0 + u * NGW; tt[u] = t; const int tc = t < TT ? t : TT - 1;
;                 const int b = tc / LL, p = tc - b * LL;
;                 const float* src = (p < NMETA) ? P.meta + (size_t)p * 1024 : P.x + ((size_t)b * SEQ + p - NMETA) * 1024;
; #pragma unroll
;                 for (int j = 0; j < 4; ++j) { const u32x2 mq = __builtin_nontemporal_load((const u32x2*)(MIX + (size_t)tc * 1024) + lane + 64 * j);
;                     m[u][j] = (f32x4){bflo(mq.x), bfhi(mq.x), bflo(mq.y), bfhi(mq.y)}; xv[u][j] = __builtin_nontemporal_load((const f32x4*)src + lane + 64 * j); } }
; #pragma unroll
;             for (int u = 0; u < 2; ++u) { const int t = tt[u]; if (t >= TT) continue;
;                 float s = 0.f; f32x4 hv[4];
; #pragma unroll
;                 for (int j = 0; j < 4; ++j) s += (m[u][j].x * m[u][j].x + m[u][j].y * m[u][j].y) + (m[u][j].z * m[u][j].z + m[u][j].w * m[u][j].w);
;                 const float rs = 1.f / sqrtf(wave_sum(s) * (1.f / 1024.f) + EPS);
; #pragma unroll
;                 for (int j = 0; j < 4; ++j) { const f32x4 gg = *((const f32x4*)P.mix_post_g + lane + 64 * j);
;                     hv[j] = xv[u][j] + m[u][j] * rs * gg; u32x2 hq; hq.x = pk2(hv[j].x, hv[j].y); hq.y = pk2(hv[j].z, hv[j].w); __builtin_nontemporal_store(hq, (u32x2*)(H1 + (size_t)t * 1024) + lane + 64 * j); }
.LBB0_806:
	s_waitcnt vmcnt(5)
	v_and_b32_e32 v63, 0xffff0000, v6
	v_and_b32_e32 v65, 0xffff0000, v7
	v_lshlrev_b32_e32 v62, 16, v6
	v_lshlrev_b32_e32 v64, 16, v7
	s_waitcnt vmcnt(4)
	v_lshlrev_b32_e32 v66, 16, v4
	v_and_b32_e32 v69, 0xffff0000, v5
	v_and_b32_e32 v68, 0xffff0000, v4
	s_waitcnt vmcnt(2)
	v_lshlrev_b32_e32 v75, 16, v0
	v_and_b32_e32 v77, 0xffff0000, v0
	v_mul_f32_e32 v0, v65, v65
	v_mul_f32_e32 v4, v63, v63
	v_lshlrev_b32_e32 v67, 16, v5
	v_lshlrev_b32_e32 v70, 16, v2
	v_and_b32_e32 v71, 0xffff0000, v2
	v_lshlrev_b32_e32 v72, 16, v3
	v_and_b32_e32 v73, 0xffff0000, v3
	v_lshlrev_b32_e32 v78, 16, v1
	v_and_b32_e32 v79, 0xffff0000, v1
	v_pk_fma_f32 v[0:1], v[64:65], v[64:65], v[0:1] op_sel_hi:[1,1,0]
	v_pk_mul_f32 v[2:3], v[68:69], v[68:69]
	v_pk_fma_f32 v[4:5], v[62:63], v[62:63], v[4:5] op_sel_hi:[1,1,0]
	v_pk_fma_f32 v[2:3], v[66:67], v[66:67], v[2:3]
	v_mov_b32_e32 v74, v4
	v_mov_b32_e32 v6, v0
	v_mov_b32_e32 v7, v75
	v_mul_f32_e32 v8, v77, v77
	v_pk_add_f32 v[0:1], v[4:5], v[0:1]
	v_pk_mul_f32 v[4:5], v[74:75], v[6:7]
	v_pk_add_f32 v[2:3], v[2:3], v[2:3] op_sel:[0,1] op_sel_hi:[1,0]
	v_mov_b32_e32 v1, v5
	v_mov_b32_e32 v3, v8
	v_pk_add_f32 v[0:1], v[0:1], v[2:3]
	v_mul_f32_e32 v2, v71, v71
	v_mul_f32_e32 v4, v73, v73
	v_mul_f32_e32 v9, v78, v78
	v_mul_f32_e32 v10, v79, v79
	v_pk_fma_f32 v[2:3], v[70:71], v[70:71], v[2:3] op_sel_hi:[1,1,0]
	v_pk_fma_f32 v[4:5], v[72:73], v[72:73], v[4:5] op_sel_hi:[1,1,0]
	v_mov_b32_e32 v3, v9
	v_mov_b32_e32 v5, v10
	v_pk_add_f32 v[2:3], v[2:3], v[4:5]
	s_ashr_i32 s5, s4, 31
	v_pk_add_f32 v[0:1], v[0:1], v[2:3]
	s_lshl_b64 s[4:5], s[4:5], 11
	v_add_f32_e32 v0, v0, v1
	ds_bpermute_b32 v1, v50, v0
	v_lshl_add_u64 v[80:81], v[32:33], 0, s[4:5]
	v_lshl_add_u64 v[82:83], v[152:153], 4, s[14:15]
	global_load_dwordx4 v[12:15], v[82:83], off nt
	global_load_dwordx4 v[4:7], v[82:83], off offset:1024 nt
	s_cmp_gt_i32 s8, 0x807f
	s_waitcnt lgkmcnt(0)
	v_add_f32_e32 v0, v0, v1
	ds_bpermute_b32 v1, v51, v0
	s_waitcnt lgkmcnt(0)
	v_add_f32_e32 v0, v0, v1
	ds_bpermute_b32 v1, v52, v0
	s_waitcnt lgkmcnt(0)
	v_add_f32_e32 v0, v0, v1
	ds_bpermute_b32 v1, v53, v0
	s_waitcnt lgkmcnt(0)
	v_add_f32_e32 v0, v0, v1
	ds_bpermute_b32 v1, v54, v0
	s_waitcnt lgkmcnt(0)
	v_add_f32_e32 v0, v0, v1
	ds_bpermute_b32 v1, v55, v0
	s_waitcnt lgkmcnt(0)
	v_add_f32_e32 v0, v0, v1
	v_fmamk_f32 v0, v0, 0x3a800000, v56
	v_mul_f32_e32 v1, 0x4f800000, v0
	v_cmp_gt_f32_e32 vcc, s21, v0
	s_nop 1
	v_cndmask_b32_e32 v0, v0, v1, vcc
	v_sqrt_f32_e32 v1, v0
	s_nop 0
	v_add_u32_e32 v2, -1, v1
	v_fma_f32 v3, -v2, v1, v0
	v_cmp_ge_f32_e64 s[4:5], 0, v3
	v_add_u32_e32 v3, 1, v1
	s_nop 0
	v_cndmask_b32_e64 v2, v1, v2, s[4:5]
	v_fma_f32 v1, -v3, v1, v0
	v_cmp_lt_f32_e64 s[4:5], 0, v1
	s_nop 1
	v_cndmask_b32_e64 v1, v2, v3, s[4:5]
	v_mul_f32_e32 v2, 0x37800000, v1
	v_cndmask_b32_e32 v1, v1, v2, vcc
	v_cmp_class_f32_e32 vcc, v0, v57
	s_nop 1
	v_cndmask_b32_e32 v74, v1, v0, vcc
	v_div_scale_f32 v76, s[4:5], v74, v74, 1.0
	v_rcp_f32_e32 v84, v76
	global_load_dwordx2 v[46:47], v[80:81], off nt
	global_load_dwordx2 v[44:45], v[80:81], off offset:512 nt
	global_load_dwordx2 v[42:43], v[80:81], off offset:1024 nt
	global_load_dwordx2 v[48:49], v[80:81], off offset:1536 nt
	global_load_dwordx4 v[8:11], v[82:83], off offset:2048 nt
	global_load_dwordx4 v[0:3], v[82:83], off offset:3072 nt
	v_fma_f32 v80, -v76, v84, 1.0
	v_fmac_f32_e32 v84, v80, v84
	v_div_scale_f32 v80, vcc, 1.0, v74, 1.0
	v_mul_f32_e32 v81, v80, v84
	v_fma_f32 v82, -v76, v81, v80
	v_fmac_f32_e32 v81, v82, v84
	v_fma_f32 v76, -v76, v81, v80
	v_div_fmas_f32 v76, v76, v84, v81
	v_div_fixup_f32 v74, v76, v74, 1.0
	v_pk_mul_f32 v[62:63], v[74:75], v[62:63] op_sel_hi:[0,1]
	v_pk_mul_f32 v[64:65], v[74:75], v[64:65] op_sel_hi:[0,1]
	s_waitcnt vmcnt(8)
	v_pk_fma_f32 v[60:61], v[98:99], v[64:65], v[30:31]
	v_pk_fma_f32 v[58:59], v[96:97], v[62:63], v[28:29]
	v_lshl_add_u64 v[80:81], v[36:37], 0, s[12:13]
	v_cvt_pk_bf16_f32 v28, v58, v59
	v_cvt_pk_bf16_f32 v29, v60, v61
	global_store_dwordx2 v[80:81], v[28:29], off nt
	v_mov_b32_e32 v62, v66
	v_mov_b32_e32 v63, v68
	v_mov_b32_e32 v68, v67
	v_pk_mul_f32 v[62:63], v[74:75], v[62:63] op_sel_hi:[0,1]
	v_pk_mul_f32 v[64:65], v[74:75], v[68:69] op_sel_hi:[0,1]
	v_mov_b32_e32 v76, v75
	v_pk_mul_f32 v[66:67], v[60:61], v[60:61]
	v_pk_mul_f32 v[68:69], v[58:59], v[58:59]
	v_pk_fma_f32 v[30:31], v[102:103], v[64:65], v[26:27]
	v_pk_fma_f32 v[28:29], v[100:101], v[62:63], v[24:25]
	v_cvt_pk_bf16_f32 v25, v30, v31
	v_cvt_pk_bf16_f32 v24, v28, v29
	global_store_dwordx2 v[80:81], v[24:25], off offset:512 nt
	v_pk_mul_f32 v[62:63], v[74:75], v[70:71] op_sel_hi:[0,1]
	v_pk_mul_f32 v[64:65], v[74:75], v[72:73] op_sel_hi:[0,1]
	v_pk_mov_b32 v[70:71], v[68:69], v[66:67] op_sel:[1,0]
	v_mov_b32_e32 v69, v67
	v_pk_add_f32 v[66:67], v[70:71], v[68:69]
	v_pk_mul_f32 v[68:69], v[28:29], v[28:29]
	v_pk_mul_f32 v[70:71], v[30:31], v[30:31]
	v_pk_add_f32 v[66:67], v[66:67], v[66:67] op_sel_hi:[0,1]
	v_pk_mov_b32 v[72:73], v[68:69], v[70:71] op_sel:[1,0]
	v_mov_b32_e32 v69, v71
	v_pk_add_f32 v[68:69], v[72:73], v[68:69]
	v_pk_fma_f32 v[26:27], v[106:107], v[64:65], v[22:23]
	v_pk_fma_f32 v[24:25], v[104:105], v[62:63], v[20:21]
	v_cvt_pk_bf16_f32 v21, v26, v27
	v_cvt_pk_bf16_f32 v20, v24, v25
	global_store_dwordx2 v[80:81], v[20:21], off offset:1024 nt
	v_pk_mul_f32 v[62:63], v[74:75], v[76:77] op_sel_hi:[0,1]
	v_pk_mul_f32 v[64:65], v[74:75], v[78:79] op_sel_hi:[0,1]
	v_pk_add_f32 v[68:69], v[68:69], v[68:69] op_sel_hi:[0,1]
	v_mul_f32_e32 v66, v24, v24
	v_mul_f32_e32 v68, v26, v26
	v_pk_fma_f32 v[70:71], v[24:25], v[24:25], v[66:67] op_sel_hi:[1,1,0]
	v_pk_fma_f32 v[72:73], v[26:27], v[26:27], v[68:69] op_sel_hi:[1,1,0]
	v_pk_fma_f32 v[22:23], v[110:111], v[64:65], v[18:19]
	v_pk_fma_f32 v[20:21], v[108:109], v[62:63], v[16:17]
	v_cvt_pk_bf16_f32 v17, v22, v23
	v_cvt_pk_bf16_f32 v16, v20, v21
	global_store_dwordx2 v[80:81], v[16:17], off offset:1536 nt
	v_mul_f32_e32 v70, v20, v20
	v_mul_f32_e32 v72, v21, v21
	v_mul_f32_e32 v66, v22, v22
	v_mul_f32_e32 v68, v23, v23
	v_pk_add_f32 v[62:63], v[70:71], v[72:73]
	v_pk_add_f32 v[64:65], v[66:67], v[68:69]
	s_nop 0
	v_pk_add_f32 v[62:63], v[62:63], v[64:65]
	s_nop 0
	v_add_f32_e32 v62, v62, v63
	ds_bpermute_b32 v63, v50, v62
	s_waitcnt lgkmcnt(0)
; __device__ __forceinline__ void rms_store_bf16(const f32x4 (&v)[4], const float* g, bf16_t* orow, int lane) {
;     float s = 0.f;
; #pragma unroll
;     for (int j = 0; j < 4; ++j) s += (v[j].x * v[j].x + v[j].y * v[j].y) + (v[j].z * v[j].z + v[j].w * v[j].w);
;     const float rs = 1.f / sqrtf(wave_sum(s) * (1.f / 1024.f) + EPS);
;     unsigned long long* o8 = (unsigned long long*)orow + lane;
; #pragma unroll
;     for (int j = 0; j < 4; ++j) { const f32x4 gg = *((const f32x4*)g + lane + 64 * j);
;         o8[64 * j] = (unsigned long long)pk2(v[j].x * rs * gg.x, v[j].y * rs * gg.y) | ((unsigned long long)pk2(v[j].z * rs * gg.z, v[j].w * rs * gg.w) << 32); }
; __global__ void __launch_bounds__(NTHR, 2) hymba_fwd(Params P) {
;     ...
;                 for (int j = 0; j < 4; ++j) s += (m[u][j].x * m[u][j].x + m[u][j].y * m[u][j].y) + (m[u][j].z * m[u][j].z + m[u][j].w * m[u][j].w);
;                 const float rs = 1.f / sqrtf(wave_sum(s) * (1.f / 1024.f) + EPS);
; #pragma unroll
;                 for (int j = 0; j < 4; ++j) { const f32x4 gg = *((const f32x4*)P.mix_post_g + lane + 64 * j);
;                     hv[j] = xv[u][j] + m[u][j] * rs * gg; u32x2 hq; hq.x = pk2(hv[j].x, hv[j].y); hq.y = pk2(hv[j].z, hv[j].w); __builtin_nontemporal_store(hq, (u32x2*)(H1 + (size_t)t * 1024) + lane + 64 * j); }
;                 rms_store_bf16(hv, P.ffn_pre_g, XN + (size_t)t * 1024, lane);
	v_add_f32_e32 v62, v62, v63
	ds_bpermute_b32 v63, v51, v62
	s_waitcnt lgkmcnt(0)
	v_add_f32_e32 v62, v62, v63
	ds_bpermute_b32 v63, v52, v62
	s_waitcnt lgkmcnt(0)
	v_add_f32_e32 v62, v62, v63
	ds_bpermute_b32 v63, v53, v62
	s_waitcnt lgkmcnt(0)
	v_add_f32_e32 v62, v62, v63
	ds_bpermute_b32 v63, v54, v62
	s_waitcnt lgkmcnt(0)
	v_add_f32_e32 v62, v62, v63
	ds_bpermute_b32 v63, v55, v62
	s_waitcnt lgkmcnt(0)
	v_add_f32_e32 v62, v62, v63
	v_fmamk_f32 v62, v62, 0x3a800000, v56
	v_mul_f32_e32 v63, 0x4f800000, v62
	v_cmp_gt_f32_e32 vcc, s21, v62
	s_nop 1
	v_cndmask_b32_e32 v62, v62, v63, vcc
	v_sqrt_f32_e32 v63, v62
	s_nop 0
	v_add_u32_e32 v64, -1, v63
	v_add_u32_e32 v65, 1, v63
	v_fma_f32 v66, -v64, v63, v62
	v_fma_f32 v67, -v65, v63, v62
	v_cmp_ge_f32_e64 s[4:5], 0, v66
	s_nop 1
	v_cndmask_b32_e64 v63, v63, v64, s[4:5]
	v_cmp_lt_f32_e64 s[4:5], 0, v67
	s_nop 1
	v_cndmask_b32_e64 v63, v63, v65, s[4:5]
	v_mul_f32_e32 v64, 0x37800000, v63
	v_cndmask_b32_e32 v63, v63, v64, vcc
	v_cmp_class_f32_e32 vcc, v62, v57
	s_nop 1
	v_cndmask_b32_e32 v64, v63, v62, vcc
	v_div_scale_f32 v65, s[4:5], v64, v64, 1.0
	v_rcp_f32_e32 v66, v65
	v_div_scale_f32 v67, vcc, 1.0, v64, 1.0
	v_lshl_add_u64 v[62:63], v[38:39], 0, s[12:13]
	v_fma_f32 v68, -v65, v66, 1.0
	v_fmac_f32_e32 v66, v68, v66
	v_mul_f32_e32 v68, v67, v66
	v_fma_f32 v69, -v65, v68, v67
	v_fmac_f32_e32 v68, v69, v66
	v_fma_f32 v65, -v65, v68, v67
	v_div_fmas_f32 v65, v65, v66, v68
	v_div_fixup_f32 v64, v65, v64, 1.0
	v_pk_mul_f32 v[58:59], v[58:59], v[64:65] op_sel_hi:[1,0]
	v_pk_mul_f32 v[60:61], v[60:61], v[64:65] op_sel_hi:[1,0]
	v_pk_mul_f32 v[16:17], v[112:113], v[58:59]
	v_pk_mul_f32 v[18:19], v[114:115], v[60:61]
	v_cvt_pk_bf16_f32 v16, v16, v17
	v_cvt_pk_bf16_f32 v17, v18, v19
	global_store_dwordx2 v[62:63], v[16:17], off
	v_pk_mul_f32 v[28:29], v[28:29], v[64:65] op_sel_hi:[1,0]
	v_pk_mul_f32 v[30:31], v[30:31], v[64:65] op_sel_hi:[1,0]
	v_pk_mul_f32 v[24:25], v[24:25], v[64:65] op_sel_hi:[1,0]
	v_pk_mul_f32 v[26:27], v[26:27], v[64:65] op_sel_hi:[1,0]
	v_pk_mul_f32 v[20:21], v[20:21], v[64:65] op_sel_hi:[1,0]
	v_pk_mul_f32 v[22:23], v[22:23], v[64:65] op_sel_hi:[1,0]
	v_pk_mul_f32 v[16:17], v[116:117], v[28:29]
	v_pk_mul_f32 v[18:19], v[118:119], v[30:31]
	v_cvt_pk_bf16_f32 v16, v16, v17
	v_cvt_pk_bf16_f32 v17, v18, v19
	global_store_dwordx2 v[62:63], v[16:17], off offset:512
	v_pk_mul_f32 v[16:17], v[120:121], v[24:25]
	v_pk_mul_f32 v[18:19], v[122:123], v[26:27]
	v_cvt_pk_bf16_f32 v16, v16, v17
	v_cvt_pk_bf16_f32 v17, v18, v19
	global_store_dwordx2 v[62:63], v[16:17], off offset:1024
	v_pk_mul_f32 v[16:17], v[20:21], v[124:125]
	v_pk_mul_f32 v[18:19], v[22:23], v[126:127]
	v_cvt_pk_bf16_f32 v16, v16, v17
	v_cvt_pk_bf16_f32 v17, v18, v19
	global_store_dwordx2 v[62:63], v[16:17], off offset:1536
	s_cbranch_scc1 .LBB0_797
	s_waitcnt vmcnt(8)
	v_and_b32_e32 v27, 0xffff0000, v46
	v_and_b32_e32 v29, 0xffff0000, v47
	v_lshlrev_b32_e32 v21, 16, v48
	v_lshlrev_b32_e32 v26, 16, v46
	v_lshlrev_b32_e32 v28, 16, v47
	v_mul_f32_e32 v16, v29, v29
	v_lshlrev_b32_e32 v31, 16, v45
	v_lshlrev_b32_e32 v30, 16, v44
	v_and_b32_e32 v45, 0xffff0000, v45
	v_and_b32_e32 v44, 0xffff0000, v44
	v_mul_f32_e32 v20, v27, v27
	v_and_b32_e32 v23, 0xffff0000, v48
	v_lshlrev_b32_e32 v24, 16, v49
	v_and_b32_e32 v25, 0xffff0000, v49
	v_pk_fma_f32 v[16:17], v[28:29], v[28:29], v[16:17] op_sel_hi:[1,1,0]
	v_pk_mul_f32 v[18:19], v[44:45], v[44:45]
	v_pk_fma_f32 v[48:49], v[26:27], v[26:27], v[20:21] op_sel_hi:[1,1,0]
	v_pk_fma_f32 v[18:19], v[30:31], v[30:31], v[18:19]
	v_mov_b32_e32 v20, v48
	v_mov_b32_e32 v58, v16
	v_mov_b32_e32 v59, v21
	v_mul_f32_e32 v22, v23, v23
	v_pk_add_f32 v[16:17], v[48:49], v[16:17]
	v_pk_mul_f32 v[48:49], v[20:21], v[58:59]
	v_pk_add_f32 v[18:19], v[18:19], v[18:19] op_sel:[0,1] op_sel_hi:[1,0]
	v_lshlrev_b32_e32 v46, 16, v42
	v_and_b32_e32 v47, 0xffff0000, v42
	v_lshlrev_b32_e32 v42, 16, v43
	v_and_b32_e32 v43, 0xffff0000, v43
	v_mov_b32_e32 v17, v49
	v_mov_b32_e32 v19, v22
	v_pk_add_f32 v[16:17], v[16:17], v[18:19]
	v_mul_f32_e32 v18, v47, v47
	v_mul_f32_e32 v20, v43, v43
	v_mul_f32_e32 v60, v24, v24
	v_mul_f32_e32 v61, v25, v25
	v_pk_fma_f32 v[18:19], v[46:47], v[46:47], v[18:19] op_sel_hi:[1,1,0]
	v_pk_fma_f32 v[48:49], v[42:43], v[42:43], v[20:21] op_sel_hi:[1,1,0]
	v_mov_b32_e32 v19, v60
	v_mov_b32_e32 v49, v61
	v_pk_add_f32 v[18:19], v[18:19], v[48:49]
	s_ashr_i32 s9, s8, 31
	v_pk_add_f32 v[48:49], v[16:17], v[18:19]
	v_add_f32_e32 v20, v48, v49
	ds_bpermute_b32 v22, v50, v20
	s_lshl_b64 s[8:9], s[8:9], 11
	s_waitcnt lgkmcnt(0)
	v_add_f32_e32 v20, v20, v22
	ds_bpermute_b32 v22, v51, v20
	s_waitcnt lgkmcnt(0)
	v_add_f32_e32 v20, v20, v22
	ds_bpermute_b32 v22, v52, v20
	s_waitcnt lgkmcnt(0)
	v_add_f32_e32 v20, v20, v22
	ds_bpermute_b32 v22, v53, v20
	s_waitcnt lgkmcnt(0)
	v_add_f32_e32 v20, v20, v22
	ds_bpermute_b32 v22, v54, v20
	s_waitcnt lgkmcnt(0)
	v_add_f32_e32 v20, v20, v22
	ds_bpermute_b32 v22, v55, v20
	s_waitcnt lgkmcnt(0)
; __device__ __forceinline__ void rms_store_bf16(const f32x4 (&v)[4], const float* g, bf16_t* orow, int lane) {
;     float s = 0.f;
; #pragma unroll
;     for (int j = 0; j < 4; ++j) s += (v[j].x * v[j].x + v[j].y * v[j].y) + (v[j].z * v[j].z + v[j].w * v[j].w);
;     const float rs = 1.f / sqrtf(wave_sum(s) * (1.f / 1024.f) + EPS);
;     unsigned long long* o8 = (unsigned long long*)orow + lane;
; #pragma unroll
;     for (int j = 0; j < 4; ++j) { const f32x4 gg = *((const f32x4*)g + lane + 64 * j);
;         o8[64 * j] = (unsigned long long)pk2(v[j].x * rs * gg.x, v[j].y * rs * gg.y) | ((unsigned long long)pk2(v[j].z * rs * gg.z, v[j].w * rs * gg.w) << 32); }
; __global__ void __launch_bounds__(NTHR, 2) hymba_fwd(Params P) {
;     ...
;                 const float rs = 1.f / sqrtf(wave_sum(s) * (1.f / 1024.f) + EPS);
; #pragma unroll
;                 for (int j = 0; j < 4; ++j) { const f32x4 gg = *((const f32x4*)P.mix_post_g + lane + 64 * j);
;                     hv[j] = xv[u][j] + m[u][j] * rs * gg; u32x2 hq; hq.x = pk2(hv[j].x, hv[j].y); hq.y = pk2(hv[j].z, hv[j].w); __builtin_nontemporal_store(hq, (u32x2*)(H1 + (size_t)t * 1024) + lane + 64 * j); }
;                 rms_store_bf16(hv, P.ffn_pre_g, XN + (size_t)t * 1024, lane);
	v_add_f32_e32 v20, v20, v22
	v_fmamk_f32 v20, v20, 0x3a800000, v56
	v_mul_f32_e32 v22, 0x4f800000, v20
	v_cmp_gt_f32_e32 vcc, s21, v20
	s_nop 1
	v_cndmask_b32_e32 v20, v20, v22, vcc
	v_sqrt_f32_e32 v22, v20
	s_nop 0
	v_add_u32_e32 v48, -1, v22
	v_fma_f32 v49, -v48, v22, v20
	v_cmp_ge_f32_e64 s[4:5], 0, v49
	v_add_u32_e32 v49, 1, v22
	s_nop 0
	v_cndmask_b32_e64 v48, v22, v48, s[4:5]
	v_fma_f32 v22, -v49, v22, v20
	v_cmp_lt_f32_e64 s[4:5], 0, v22
	s_nop 1
	v_cndmask_b32_e64 v22, v48, v49, s[4:5]
	v_mul_f32_e32 v48, 0x37800000, v22
	v_cndmask_b32_e32 v22, v22, v48, vcc
	v_cmp_class_f32_e32 vcc, v20, v57
	s_nop 1
	v_cndmask_b32_e32 v20, v22, v20, vcc
	v_div_scale_f32 v22, s[4:5], v20, v20, 1.0
	v_rcp_f32_e32 v48, v22
	s_nop 0
	v_fma_f32 v49, -v22, v48, 1.0
	v_fmac_f32_e32 v48, v49, v48
	v_div_scale_f32 v49, vcc, 1.0, v20, 1.0
	v_mul_f32_e32 v58, v49, v48
	v_fma_f32 v59, -v22, v58, v49
	v_fmac_f32_e32 v58, v59, v48
	v_fma_f32 v22, -v22, v58, v49
	v_div_fmas_f32 v22, v22, v48, v58
	v_div_fixup_f32 v20, v22, v20, 1.0
	v_pk_mul_f32 v[26:27], v[20:21], v[26:27] op_sel_hi:[0,1]
	v_pk_mul_f32 v[28:29], v[20:21], v[28:29] op_sel_hi:[0,1]
	v_pk_fma_f32 v[18:19], v[98:99], v[28:29], v[14:15]
	v_pk_fma_f32 v[16:17], v[96:97], v[26:27], v[12:13]
	v_lshl_add_u64 v[48:49], v[36:37], 0, s[8:9]
	v_cvt_pk_bf16_f32 v12, v16, v17
	v_cvt_pk_bf16_f32 v13, v18, v19
	global_store_dwordx2 v[48:49], v[12:13], off nt
	v_mov_b32_e32 v26, v30
	v_mov_b32_e32 v27, v44
	v_mov_b32_e32 v44, v31
	v_pk_mul_f32 v[26:27], v[20:21], v[26:27] op_sel_hi:[0,1]
	v_pk_mul_f32 v[28:29], v[20:21], v[44:45] op_sel_hi:[0,1]
	v_mov_b32_e32 v22, v21
	v_pk_mul_f32 v[22:23], v[20:21], v[22:23] op_sel_hi:[0,1]
	v_pk_fma_f32 v[14:15], v[102:103], v[28:29], v[6:7]
	v_pk_fma_f32 v[12:13], v[100:101], v[26:27], v[4:5]
	v_cvt_pk_bf16_f32 v5, v14, v15
	v_cvt_pk_bf16_f32 v4, v12, v13
	global_store_dwordx2 v[48:49], v[4:5], off offset:512 nt
	v_pk_mul_f32 v[26:27], v[20:21], v[46:47] op_sel_hi:[0,1]
	v_pk_mul_f32 v[28:29], v[20:21], v[42:43] op_sel_hi:[0,1]
	v_pk_mul_f32 v[20:21], v[20:21], v[24:25] op_sel_hi:[0,1]
	v_pk_mul_f32 v[24:25], v[18:19], v[18:19]
	v_pk_fma_f32 v[10:11], v[106:107], v[28:29], v[10:11]
	v_pk_fma_f32 v[8:9], v[104:105], v[26:27], v[8:9]
	v_cvt_pk_bf16_f32 v5, v10, v11
	v_cvt_pk_bf16_f32 v4, v8, v9
	global_store_dwordx2 v[48:49], v[4:5], off offset:1024 nt
	v_pk_mul_f32 v[26:27], v[16:17], v[16:17]
	v_pk_fma_f32 v[6:7], v[110:111], v[20:21], v[2:3]
	v_pk_fma_f32 v[4:5], v[108:109], v[22:23], v[0:1]
	v_cvt_pk_bf16_f32 v1, v6, v7
	v_cvt_pk_bf16_f32 v0, v4, v5
	global_store_dwordx2 v[48:49], v[0:1], off offset:1536 nt
	v_pk_mov_b32 v[28:29], v[26:27], v[24:25] op_sel:[1,0]
	v_mov_b32_e32 v27, v25
	v_pk_add_f32 v[24:25], v[28:29], v[26:27]
	v_pk_mul_f32 v[26:27], v[12:13], v[12:13]
	v_pk_mul_f32 v[28:29], v[14:15], v[14:15]
	v_pk_add_f32 v[24:25], v[24:25], v[24:25] op_sel_hi:[0,1]
	v_pk_mov_b32 v[30:31], v[26:27], v[28:29] op_sel:[1,0]
	v_mov_b32_e32 v27, v29
	v_pk_add_f32 v[26:27], v[30:31], v[26:27]
	v_mul_f32_e32 v24, v8, v8
	v_pk_add_f32 v[26:27], v[26:27], v[26:27] op_sel_hi:[0,1]
	v_mul_f32_e32 v26, v10, v10
	v_pk_fma_f32 v[28:29], v[8:9], v[8:9], v[24:25] op_sel_hi:[1,1,0]
	v_pk_fma_f32 v[30:31], v[10:11], v[10:11], v[26:27] op_sel_hi:[1,1,0]
	v_mul_f32_e32 v28, v4, v4
	v_mul_f32_e32 v30, v5, v5
	v_mul_f32_e32 v24, v6, v6
	v_mul_f32_e32 v26, v7, v7
	v_pk_add_f32 v[20:21], v[28:29], v[30:31]
	v_pk_add_f32 v[22:23], v[24:25], v[26:27]
	s_nop 0
	v_pk_add_f32 v[20:21], v[20:21], v[22:23]
	s_nop 0
	v_add_f32_e32 v20, v20, v21
	ds_bpermute_b32 v21, v50, v20
	s_waitcnt lgkmcnt(0)
	v_add_f32_e32 v20, v20, v21
	ds_bpermute_b32 v21, v51, v20
	s_waitcnt lgkmcnt(0)
	v_add_f32_e32 v20, v20, v21
	ds_bpermute_b32 v21, v52, v20
	s_waitcnt lgkmcnt(0)
	v_add_f32_e32 v20, v20, v21
	ds_bpermute_b32 v21, v53, v20
	s_waitcnt lgkmcnt(0)
	v_add_f32_e32 v20, v20, v21
	ds_bpermute_b32 v21, v54, v20
	s_waitcnt lgkmcnt(0)
	v_add_f32_e32 v20, v20, v21
	ds_bpermute_b32 v21, v55, v20
	s_waitcnt lgkmcnt(0)
	v_add_f32_e32 v20, v20, v21
	v_fmamk_f32 v20, v20, 0x3a800000, v56
	v_mul_f32_e32 v21, 0x4f800000, v20
	v_cmp_gt_f32_e32 vcc, s21, v20
	s_nop 1
	v_cndmask_b32_e32 v20, v20, v21, vcc
	v_sqrt_f32_e32 v21, v20
	s_nop 0
	v_add_u32_e32 v22, -1, v21
	v_add_u32_e32 v23, 1, v21
	v_fma_f32 v24, -v22, v21, v20
	v_fma_f32 v25, -v23, v21, v20
	v_cmp_ge_f32_e64 s[4:5], 0, v24
	s_nop 1
	v_cndmask_b32_e64 v21, v21, v22, s[4:5]
	v_cmp_lt_f32_e64 s[4:5], 0, v25
	s_nop 1
	v_cndmask_b32_e64 v21, v21, v23, s[4:5]
	v_mul_f32_e32 v22, 0x37800000, v21
	v_cndmask_b32_e32 v21, v21, v22, vcc
	v_cmp_class_f32_e32 vcc, v20, v57
	s_nop 1
	v_cndmask_b32_e32 v22, v21, v20, vcc
	v_div_scale_f32 v23, s[4:5], v22, v22, 1.0
	v_rcp_f32_e32 v24, v23
	v_div_scale_f32 v25, vcc, 1.0, v22, 1.0
	v_lshl_add_u64 v[20:21], v[38:39], 0, s[8:9]
	v_fma_f32 v26, -v23, v24, 1.0
	v_fmac_f32_e32 v24, v26, v24
	v_mul_f32_e32 v26, v25, v24
	v_fma_f32 v27, -v23, v26, v25
	v_fmac_f32_e32 v26, v27, v24
	v_fma_f32 v23, -v23, v26, v25
	v_div_fmas_f32 v23, v23, v24, v26
	v_div_fixup_f32 v22, v23, v22, 1.0
	v_pk_mul_f32 v[16:17], v[16:17], v[22:23] op_sel_hi:[1,0]
	v_pk_mul_f32 v[18:19], v[18:19], v[22:23] op_sel_hi:[1,0]
	v_pk_mul_f32 v[0:1], v[112:113], v[16:17]
	v_pk_mul_f32 v[2:3], v[114:115], v[18:19]
	v_cvt_pk_bf16_f32 v0, v0, v1
	v_cvt_pk_bf16_f32 v1, v2, v3
	global_store_dwordx2 v[20:21], v[0:1], off
	v_pk_mul_f32 v[12:13], v[12:13], v[22:23] op_sel_hi:[1,0]
	v_pk_mul_f32 v[14:15], v[14:15], v[22:23] op_sel_hi:[1,0]
	v_pk_mul_f32 v[8:9], v[8:9], v[22:23] op_sel_hi:[1,0]
	v_pk_mul_f32 v[10:11], v[10:11], v[22:23] op_sel_hi:[1,0]
	v_pk_mul_f32 v[4:5], v[4:5], v[22:23] op_sel_hi:[1,0]
	v_pk_mul_f32 v[6:7], v[6:7], v[22:23] op_sel_hi:[1,0]
	v_pk_mul_f32 v[0:1], v[116:117], v[12:13]
	v_pk_mul_f32 v[2:3], v[118:119], v[14:15]
	v_cvt_pk_bf16_f32 v0, v0, v1
	v_cvt_pk_bf16_f32 v1, v2, v3
	global_store_dwordx2 v[20:21], v[0:1], off offset:512
	v_pk_mul_f32 v[0:1], v[120:121], v[8:9]
	v_pk_mul_f32 v[2:3], v[122:123], v[10:11]
	v_cvt_pk_bf16_f32 v0, v0, v1
	v_cvt_pk_bf16_f32 v1, v2, v3
	global_store_dwordx2 v[20:21], v[0:1], off offset:1024
	v_pk_mul_f32 v[0:1], v[4:5], v[124:125]
	v_pk_mul_f32 v[2:3], v[6:7], v[126:127]
	v_cvt_pk_bf16_f32 v0, v0, v1
	v_cvt_pk_bf16_f32 v1, v2, v3
	global_store_dwordx2 v[20:21], v[0:1], off offset:1536
	s_branch .LBB0_797
